# speedup vs baseline: 1.0248x; 1.0027x over previous
;   __device__ __forceinline__ void operator()(int m, int n, f32x4 v) const {
;     int b, key;
;     if (m < TX) { b = m >> 11; key = m & 2047; } else { b = (m - TX) >> 8; key = 2048 + ((m - TX) & 255); }
;     if (n >= 256 && n < 768) {
;       int c = n - 256, h = c >> 7, e = c & 127;
;       u16* d = RVT + ((size_t)(b * 4 + h) * 128 + e) * KEYS + key;
;       d[0] = f2bf(v[0]); d[KEYS] = f2bf(v[1]); d[2 * KEYS] = f2bf(v[2]); d[3 * KEYS] = f2bf(v[3]);
;       return;
;     }
;     if (n >= 896 && n < 1024) {
;       int c = n - 896, h = c >> 6, e = c & 63;
;       u16* d = SVT + ((size_t)(b * 2 + h) * 64 + e) * KEYS + key;
;       d[0] = f2bf(v[0]); d[KEYS] = f2bf(v[1]); d[2 * KEYS] = f2bf(v[2]); d[3 * KEYS] = f2bf(v[3]);
;       return;
;     }
;     if (n < 256) { v[0] *= 0.125f; v[1] *= 0.125f; v[2] *= 0.125f; v[3] *= 0.125f; }
;     if (m < TX && cd_rope_col(n)) v = rope4(v, rope, key, (n & 63) >> 1);
;     store4bf(Z + (size_t)m * 2304 + n, v);
;   }
.LBB0_109:
	s_or_b64 exec, exec, s[0:1]
	v_lshl_or_b32 v0, s12, 8, v145
	v_add_u32_e32 v139, v0, v146
	v_lshlrev_b32_e32 v0, 2, v144
	v_lshl_or_b32 v138, v143, 5, v0
	s_cmpk_eq_i32 s51, 0x100
	s_cbranch_scc1 .Lcdin_norope
	s_cmpk_eq_i32 s51, 0x200
	s_cbranch_scc1 .Lcdin_norope
	s_cmpk_eq_i32 s51, 0x500
	s_cbranch_scc1 .Lcdin_norope
	s_cmpk_eq_i32 s51, 0x600
	s_cbranch_scc1 .Lcdin_norope
	v_and_b32_e32 v224, 63, v138
	v_lshlrev_b32_e32 v224, 2, v224
	v_mov_b32_e32 v225, v139
	v_and_b32_e32 v225, 0x7ff, v225
	v_lshl_or_b32 v225, v225, 8, v224
	global_load_dwordx4 v[148:151], v225, s[40:41]
	global_load_dwordx4 v[152:155], v225, s[40:41] offset:64
	v_add_u32_e32 v225, 16, v139
	v_and_b32_e32 v225, 0x7ff, v225
	v_lshl_or_b32 v225, v225, 8, v224
	global_load_dwordx4 v[156:159], v225, s[40:41]
	global_load_dwordx4 v[160:163], v225, s[40:41] offset:64
	v_add_u32_e32 v225, 32, v139
	v_and_b32_e32 v225, 0x7ff, v225
	v_lshl_or_b32 v225, v225, 8, v224
	global_load_dwordx4 v[164:167], v225, s[40:41]
	global_load_dwordx4 v[168:171], v225, s[40:41] offset:64
	v_add_u32_e32 v225, 48, v139
	v_and_b32_e32 v225, 0x7ff, v225
	v_lshl_or_b32 v225, v225, 8, v224
	global_load_dwordx4 v[172:175], v225, s[40:41]
	global_load_dwordx4 v[176:179], v225, s[40:41] offset:64
	v_add_u32_e32 v225, 128, v139
	v_and_b32_e32 v225, 0x7ff, v225
	v_lshl_or_b32 v225, v225, 8, v224
	global_load_dwordx4 v[180:183], v225, s[40:41]
	global_load_dwordx4 v[184:187], v225, s[40:41] offset:64
	v_add_u32_e32 v225, 144, v139
	v_and_b32_e32 v225, 0x7ff, v225
	v_lshl_or_b32 v225, v225, 8, v224
	global_load_dwordx4 v[188:191], v225, s[40:41]
	global_load_dwordx4 v[192:195], v225, s[40:41] offset:64
	v_add_u32_e32 v225, 160, v139
	v_and_b32_e32 v225, 0x7ff, v225
	v_lshl_or_b32 v225, v225, 8, v224
	global_load_dwordx4 v[208:211], v225, s[40:41]
	global_load_dwordx4 v[212:215], v225, s[40:41] offset:64
	v_add_u32_e32 v225, 176, v139
	v_and_b32_e32 v225, 0x7ff, v225
	v_lshl_or_b32 v225, v225, 8, v224
	global_load_dwordx4 v[216:219], v225, s[40:41]
	global_load_dwordx4 v[220:223], v225, s[40:41] offset:64
	s_waitcnt vmcnt(0)
.Lcdin_norope:
	v_or_b32_e32 v136, s51, v138
	v_mad_i64_i32 v[130:131], s[0:1], v139, s26, 0
	v_lshrrev_b32_e32 v0, 1, v138
	v_add_u32_e32 v132, 0xffffff00, v136
	s_movk_i32 s0, 0x1ff
	v_and_b32_e32 v137, 22, v0
	v_cmp_gt_i32_e64 s[22:23], s74, v139
	v_and_b32_e32 v141, 0x7cf, v139
	v_cmp_lt_u32_e64 s[12:13], s0, v132
	s_and_saveexec_b64 s[0:1], s[12:13]
	s_xor_b64 s[0:1], exec, s[0:1]
	s_cbranch_execz .LBB0_114
	s_cmp_lt_u32 s47, 4
	v_pk_mul_f32 v[134:135], v[128:129], s[54:55] op_sel_hi:[1,0]
	v_pk_mul_f32 v[142:143], v[126:127], s[54:55] op_sel_hi:[1,0]
	s_cselect_b64 vcc, -1, 0
	v_cndmask_b32_e32 v127, v127, v143, vcc
	v_cndmask_b32_e32 v126, v126, v142, vcc
	v_cndmask_b32_e32 v129, v129, v135, vcc
	v_cndmask_b32_e32 v128, v128, v134, vcc
	s_and_saveexec_b64 s[8:9], s[22:23]
	s_cbranch_execz .LBB0_113
	s_cmpk_eq_i32 s51, 0x300
	s_cselect_b64 s[6:7], -1, 0
	s_cmpk_eq_i32 s51, 0x400
	s_cselect_b64 s[10:11], -1, 0
	s_or_b64 s[6:7], s[6:7], s[10:11]
	s_or_b64 s[6:7], vcc, s[6:7]
	s_and_b32 s10, s47, 0xffff
	s_cmp_gt_u32 s10, 27
	s_cselect_b64 s[10:11], -1, 0
	s_or_b64 s[6:7], s[6:7], s[10:11]
	s_andn2_b64 vcc, exec, s[6:7]
	s_cbranch_vccnz .LBB0_113
	v_lshlrev_b32_e32 v0, 3, v137
	v_lshl_or_b32 v0, v141, 8, v0
	v_mov_b32_e32 v142, v148
	v_mov_b32_e32 v143, v149
	v_mov_b32_e32 v144, v150
	v_mov_b32_e32 v145, v151
	v_pk_mul_f32 v[134:135], v[126:127], v[142:143] op_sel:[1,1] op_sel_hi:[0,1]
	v_mul_f32_e32 v0, v129, v145
	v_pk_mul_f32 v[146:147], v[126:127], v[142:143] op_sel_hi:[1,0]
	v_pk_fma_f32 v[126:127], v[126:127], v[142:143], v[134:135] op_sel_hi:[1,0,1]
	v_pk_fma_f32 v[142:143], v[128:129], v[144:145], v[0:1] op_sel_hi:[1,1,0] neg_lo:[0,0,1] neg_hi:[0,0,1]
	v_mul_f32_e32 v0, v128, v145
	v_pk_fma_f32 v[128:129], v[128:129], v[144:145], v[0:1] op_sel:[1,0,0] op_sel_hi:[0,1,0]
	v_sub_f32_e32 v126, v146, v134
	v_mov_b32_e32 v129, v128
	v_mov_b32_e32 v128, v142

;   __device__ __forceinline__ void operator()(int m, int n, f32x4 v) const {
;     int b, key;
;     if (m < TX) { b = m >> 11; key = m & 2047; } else { b = (m - TX) >> 8; key = 2048 + ((m - TX) & 255); }
;     if (n >= 256 && n < 768) {
;       int c = n - 256, h = c >> 7, e = c & 127;
;       u16* d = RVT + ((size_t)(b * 4 + h) * 128 + e) * KEYS + key;
;       d[0] = f2bf(v[0]); d[KEYS] = f2bf(v[1]); d[2 * KEYS] = f2bf(v[2]); d[3 * KEYS] = f2bf(v[3]);
;       return;
;     }
;     if (n >= 896 && n < 1024) {
;       int c = n - 896, h = c >> 6, e = c & 63;
;       u16* d = SVT + ((size_t)(b * 2 + h) * 64 + e) * KEYS + key;
;       d[0] = f2bf(v[0]); d[KEYS] = f2bf(v[1]); d[2 * KEYS] = f2bf(v[2]); d[3 * KEYS] = f2bf(v[3]);
;       return;
;     }
;     if (n < 256) { v[0] *= 0.125f; v[1] *= 0.125f; v[2] *= 0.125f; v[3] *= 0.125f; }
;     if (m < TX && cd_rope_col(n)) v = rope4(v, rope, key, (n & 63) >> 1);
;     store4bf(Z + (size_t)m * 2304 + n, v);
;   }
.LBB0_116:
	s_or_b64 exec, exec, s[0:1]
	v_add_u32_e32 v127, 0xffffff10, v136
	s_movk_i32 s0, 0x1ff
	v_or_b32_e32 v126, 16, v136
	v_cmp_lt_u32_e64 s[14:15], s0, v127
	s_and_saveexec_b64 s[0:1], s[14:15]
	s_xor_b64 s[0:1], exec, s[0:1]
	s_cbranch_execz .LBB0_122
	s_movk_i32 s6, 0xf0
	v_pk_mul_f32 v[128:129], v[124:125], s[54:55] op_sel_hi:[1,0]
	v_pk_mul_f32 v[134:135], v[122:123], s[54:55] op_sel_hi:[1,0]
	v_cmp_gt_u32_e32 vcc, s6, v136
	s_nop 1
	v_cndmask_b32_e32 v123, v123, v135, vcc
	v_cndmask_b32_e32 v122, v122, v134, vcc
	v_cndmask_b32_e32 v125, v125, v129, vcc
	v_cndmask_b32_e32 v124, v124, v128, vcc
	s_and_saveexec_b64 s[8:9], s[22:23]
	s_cbranch_execz .LBB0_121
	s_cmpk_eq_i32 s51, 0x300
	s_cselect_b64 s[6:7], -1, 0
	s_cmpk_eq_i32 s51, 0x400
	s_cselect_b64 s[10:11], -1, 0
	s_or_b64 s[6:7], s[6:7], s[10:11]
	s_movk_i32 s10, 0x6ef
	s_or_b64 s[6:7], s[6:7], vcc
	v_cmp_lt_u32_e32 vcc, s10, v136
	s_or_b64 s[6:7], s[6:7], vcc
	s_and_saveexec_b64 s[10:11], s[6:7]
	s_cbranch_execz .LBB0_120
	v_lshlrev_b32_e32 v0, 2, v126
	v_and_b32_e32 v0, 0xf0, v0
	v_lshl_or_b32 v0, v141, 8, v0
	v_mov_b32_e32 v144, v152
	v_mov_b32_e32 v145, v153
	v_mov_b32_e32 v146, v154
	v_mov_b32_e32 v147, v155
	v_pk_mul_f32 v[128:129], v[122:123], v[144:145] op_sel:[1,1] op_sel_hi:[0,1]
	v_mul_f32_e32 v0, v125, v147
	v_pk_mul_f32 v[134:135], v[122:123], v[144:145] op_sel_hi:[1,0]
	v_pk_fma_f32 v[122:123], v[122:123], v[144:145], v[128:129] op_sel_hi:[1,0,1]
	v_pk_fma_f32 v[144:145], v[124:125], v[146:147], v[0:1] op_sel_hi:[1,1,0] neg_lo:[0,0,1] neg_hi:[0,0,1]
	v_mul_f32_e32 v0, v124, v147
	v_pk_fma_f32 v[124:125], v[124:125], v[146:147], v[0:1] op_sel:[1,0,0] op_sel_hi:[0,1,0]
	v_sub_f32_e32 v122, v134, v128
	v_mov_b32_e32 v125, v124
	v_mov_b32_e32 v124, v144

;   __device__ __forceinline__ void operator()(int m, int n, f32x4 v) const {
;     int b, key;
;     if (m < TX) { b = m >> 11; key = m & 2047; } else { b = (m - TX) >> 8; key = 2048 + ((m - TX) & 255); }
;     if (n >= 256 && n < 768) {
;       int c = n - 256, h = c >> 7, e = c & 127;
;       u16* d = RVT + ((size_t)(b * 4 + h) * 128 + e) * KEYS + key;
;       d[0] = f2bf(v[0]); d[KEYS] = f2bf(v[1]); d[2 * KEYS] = f2bf(v[2]); d[3 * KEYS] = f2bf(v[3]);
;       return;
;     }
;     if (n >= 896 && n < 1024) {
;       int c = n - 896, h = c >> 6, e = c & 63;
;       u16* d = SVT + ((size_t)(b * 2 + h) * 64 + e) * KEYS + key;
;       d[0] = f2bf(v[0]); d[KEYS] = f2bf(v[1]); d[2 * KEYS] = f2bf(v[2]); d[3 * KEYS] = f2bf(v[3]);
;       return;
;     }
;     if (n < 256) { v[0] *= 0.125f; v[1] *= 0.125f; v[2] *= 0.125f; v[3] *= 0.125f; }
;     if (m < TX && cd_rope_col(n)) v = rope4(v, rope, key, (n & 63) >> 1);
;     store4bf(Z + (size_t)m * 2304 + n, v);
;   }
.LBB0_124:
	s_or_b64 exec, exec, s[0:1]
	s_mov_b32 s0, 0xfff0
	v_or_b32_e32 v0, 16, v139
	v_cmp_gt_i32_e64 s[20:21], s0, v139
	s_movk_i32 s0, 0x7df
	v_bitop3_b32 v128, v139, s0, 16 bitop3:0xc8
	v_mad_i64_i32 v[122:123], s[0:1], v0, s26, 0
	s_and_saveexec_b64 s[0:1], s[12:13]
	s_xor_b64 s[0:1], exec, s[0:1]
	s_cbranch_execz .LBB0_129
	s_cmp_lt_u32 s47, 4
	v_pk_mul_f32 v[124:125], v[120:121], s[54:55] op_sel_hi:[1,0]
	v_pk_mul_f32 v[134:135], v[118:119], s[54:55] op_sel_hi:[1,0]
	s_cselect_b64 vcc, -1, 0
	v_cndmask_b32_e32 v119, v119, v135, vcc
	v_cndmask_b32_e32 v118, v118, v134, vcc
	v_cndmask_b32_e32 v121, v121, v125, vcc
	v_cndmask_b32_e32 v120, v120, v124, vcc
	s_and_saveexec_b64 s[8:9], s[20:21]
	s_cbranch_execz .LBB0_128
	s_cmpk_eq_i32 s51, 0x300
	s_cselect_b64 s[6:7], -1, 0
	s_cmpk_eq_i32 s51, 0x400
	s_cselect_b64 s[10:11], -1, 0
	s_or_b64 s[6:7], s[6:7], s[10:11]
	s_or_b64 s[6:7], vcc, s[6:7]
	s_and_b32 s10, s47, 0xffff
	s_cmp_gt_u32 s10, 27
	s_cselect_b64 s[10:11], -1, 0
	s_or_b64 s[6:7], s[6:7], s[10:11]
	s_andn2_b64 vcc, exec, s[6:7]
	s_cbranch_vccnz .LBB0_128
	v_lshlrev_b32_e32 v0, 3, v137
	v_lshl_or_b32 v0, v128, 8, v0
	v_mov_b32_e32 v144, v156
	v_mov_b32_e32 v145, v157
	v_mov_b32_e32 v146, v158
	v_mov_b32_e32 v147, v159
	v_pk_mul_f32 v[124:125], v[118:119], v[144:145] op_sel:[1,1] op_sel_hi:[0,1]
	v_mul_f32_e32 v0, v121, v147
	v_pk_mul_f32 v[134:135], v[118:119], v[144:145] op_sel_hi:[1,0]
	v_pk_fma_f32 v[118:119], v[118:119], v[144:145], v[124:125] op_sel_hi:[1,0,1]
	v_pk_fma_f32 v[144:145], v[120:121], v[146:147], v[0:1] op_sel_hi:[1,1,0] neg_lo:[0,0,1] neg_hi:[0,0,1]
	v_mul_f32_e32 v0, v120, v147
	v_pk_fma_f32 v[120:121], v[120:121], v[146:147], v[0:1] op_sel:[1,0,0] op_sel_hi:[0,1,0]
	v_sub_f32_e32 v118, v134, v124
	v_mov_b32_e32 v121, v120
	v_mov_b32_e32 v120, v144

;   __device__ __forceinline__ void operator()(int m, int n, f32x4 v) const {
;     ...
;     if (n < 256) { v[0] *= 0.125f; v[1] *= 0.125f; v[2] *= 0.125f; v[3] *= 0.125f; }
;     if (m < TX && cd_rope_col(n)) v = rope4(v, rope, key, (n & 63) >> 1);
.LBB0_133:
	s_or_b64 exec, exec, s[0:1]
	s_mov_b32 s0, 0xffe0
	v_or_b32_e32 v0, 32, v139
	v_cmp_gt_i32_e64 s[18:19], s0, v139
	s_movk_i32 s0, 0x7ef
	v_bitop3_b32 v118, v139, s0, 32 bitop3:0xc8
	v_mad_i64_i32 v[114:115], s[0:1], v0, s26, 0
	s_and_saveexec_b64 s[0:1], s[12:13]
	s_xor_b64 s[0:1], exec, s[0:1]
	s_cbranch_execz .LBB0_138
	s_cmp_lt_u32 s47, 4
	v_pk_mul_f32 v[116:117], v[112:113], s[54:55] op_sel_hi:[1,0]
	v_pk_mul_f32 v[120:121], v[110:111], s[54:55] op_sel_hi:[1,0]
	s_cselect_b64 vcc, -1, 0
	v_cndmask_b32_e32 v111, v111, v121, vcc
	v_cndmask_b32_e32 v110, v110, v120, vcc
	v_cndmask_b32_e32 v113, v113, v117, vcc
	v_cndmask_b32_e32 v112, v112, v116, vcc
	s_and_saveexec_b64 s[8:9], s[18:19]
	s_cbranch_execz .LBB0_137
	s_cmpk_eq_i32 s51, 0x300
	s_cselect_b64 s[6:7], -1, 0
	s_cmpk_eq_i32 s51, 0x400
	s_cselect_b64 s[10:11], -1, 0
	s_or_b64 s[6:7], s[6:7], s[10:11]
	s_or_b64 s[6:7], vcc, s[6:7]
	s_and_b32 s10, s47, 0xffff
	s_cmp_gt_u32 s10, 27
	s_cselect_b64 s[10:11], -1, 0
	s_or_b64 s[6:7], s[6:7], s[10:11]
	s_andn2_b64 vcc, exec, s[6:7]
	s_cbranch_vccnz .LBB0_137
	v_lshlrev_b32_e32 v0, 3, v137
	v_lshl_or_b32 v0, v118, 8, v0
	v_mov_b32_e32 v144, v164
	v_mov_b32_e32 v145, v165
	v_mov_b32_e32 v146, v166
	v_mov_b32_e32 v147, v167
	v_mul_f32_e32 v0, v113, v147
	v_pk_mul_f32 v[116:117], v[110:111], v[144:145] op_sel:[1,1] op_sel_hi:[0,1]
	v_pk_fma_f32 v[134:135], v[112:113], v[146:147], v[0:1] op_sel_hi:[1,1,0] neg_lo:[0,0,1] neg_hi:[0,0,1]
	v_mul_f32_e32 v0, v112, v147
	v_pk_mul_f32 v[120:121], v[110:111], v[144:145] op_sel_hi:[1,0]
	v_pk_fma_f32 v[110:111], v[110:111], v[144:145], v[116:117] op_sel_hi:[1,0,1]
	v_pk_fma_f32 v[112:113], v[112:113], v[146:147], v[0:1] op_sel:[1,0,0] op_sel_hi:[0,1,0]
	v_sub_f32_e32 v110, v120, v116
	v_mov_b32_e32 v113, v112
	v_mov_b32_e32 v112, v134

;   __device__ __forceinline__ void operator()(int m, int n, f32x4 v) const {
;     ...
;     if (n < 256) { v[0] *= 0.125f; v[1] *= 0.125f; v[2] *= 0.125f; v[3] *= 0.125f; }
;     if (m < TX && cd_rope_col(n)) v = rope4(v, rope, key, (n & 63) >> 1);
.LBB0_142:
	s_or_b64 exec, exec, s[0:1]
	s_mov_b32 s0, 0xffd0
	v_or_b32_e32 v0, 48, v139
	v_cmp_gt_i32_e64 s[16:17], s0, v139
	s_movk_i32 s0, 0x7ff
	v_bitop3_b32 v110, v139, s0, 48 bitop3:0xc8
	v_mad_i64_i32 v[106:107], s[0:1], v0, s26, 0
	s_and_saveexec_b64 s[0:1], s[12:13]
	s_xor_b64 s[0:1], exec, s[0:1]
	s_cbranch_execz .LBB0_147
	s_cmp_lt_u32 s47, 4
	v_pk_mul_f32 v[108:109], v[104:105], s[54:55] op_sel_hi:[1,0]
	v_pk_mul_f32 v[112:113], v[102:103], s[54:55] op_sel_hi:[1,0]
	s_cselect_b64 vcc, -1, 0
	v_cndmask_b32_e32 v103, v103, v113, vcc
	v_cndmask_b32_e32 v102, v102, v112, vcc
	v_cndmask_b32_e32 v105, v105, v109, vcc
	v_cndmask_b32_e32 v104, v104, v108, vcc
	s_and_saveexec_b64 s[8:9], s[16:17]
	s_cbranch_execz .LBB0_146
	s_cmpk_eq_i32 s51, 0x300
	s_cselect_b64 s[6:7], -1, 0
	s_cmpk_eq_i32 s51, 0x400
	s_cselect_b64 s[10:11], -1, 0
	s_or_b64 s[6:7], s[6:7], s[10:11]
	s_or_b64 s[6:7], vcc, s[6:7]
	s_and_b32 s10, s47, 0xffff
	s_cmp_gt_u32 s10, 27
	s_cselect_b64 s[10:11], -1, 0
	s_or_b64 s[6:7], s[6:7], s[10:11]
	s_andn2_b64 vcc, exec, s[6:7]
	s_cbranch_vccnz .LBB0_146
	v_lshlrev_b32_e32 v0, 3, v137
	v_lshl_or_b32 v0, v110, 8, v0
	v_mov_b32_e32 v144, v172
	v_mov_b32_e32 v145, v173
	v_mov_b32_e32 v146, v174
	v_mov_b32_e32 v147, v175
	v_mul_f32_e32 v0, v105, v147
	v_pk_mul_f32 v[108:109], v[102:103], v[144:145] op_sel:[1,1] op_sel_hi:[0,1]
	v_pk_fma_f32 v[120:121], v[104:105], v[146:147], v[0:1] op_sel_hi:[1,1,0] neg_lo:[0,0,1] neg_hi:[0,0,1]
	v_mul_f32_e32 v0, v104, v147
	v_pk_mul_f32 v[112:113], v[102:103], v[144:145] op_sel_hi:[1,0]
	v_pk_fma_f32 v[102:103], v[102:103], v[144:145], v[108:109] op_sel_hi:[1,0,1]
	v_pk_fma_f32 v[104:105], v[104:105], v[146:147], v[0:1] op_sel:[1,0,0] op_sel_hi:[0,1,0]
	v_sub_f32_e32 v102, v112, v108
	v_mov_b32_e32 v105, v104
	v_mov_b32_e32 v104, v120

;   __device__ __forceinline__ void operator()(int m, int n, f32x4 v) const {
;     ...
;     if (n < 256) { v[0] *= 0.125f; v[1] *= 0.125f; v[2] *= 0.125f; v[3] *= 0.125f; }
;     if (m < TX && cd_rope_col(n)) v = rope4(v, rope, key, (n & 63) >> 1);
.LBB0_158:
	s_movk_i32 s6, 0xf0
	v_pk_mul_f32 v[118:119], v[116:117], s[54:55] op_sel_hi:[1,0]
	v_pk_mul_f32 v[120:121], v[114:115], s[54:55] op_sel_hi:[1,0]
	v_cmp_gt_u32_e32 vcc, s6, v136
	s_nop 1
	v_cndmask_b32_e32 v115, v115, v121, vcc
	v_cndmask_b32_e32 v114, v114, v120, vcc
	v_cndmask_b32_e32 v117, v117, v119, vcc
	v_cndmask_b32_e32 v116, v116, v118, vcc
	s_and_saveexec_b64 s[8:9], s[20:21]
	s_cbranch_execz .LBB0_162
	s_cmpk_eq_i32 s51, 0x300
	s_cselect_b64 s[6:7], -1, 0
	s_cmpk_eq_i32 s51, 0x400
	s_cselect_b64 s[10:11], -1, 0
	s_or_b64 s[6:7], s[6:7], s[10:11]
	s_movk_i32 s10, 0x6ef
	s_or_b64 s[6:7], s[6:7], vcc
	v_cmp_lt_u32_e32 vcc, s10, v136
	s_or_b64 s[6:7], s[6:7], vcc
	s_and_saveexec_b64 s[10:11], s[6:7]
	s_cbranch_execz .LBB0_161
	v_lshlrev_b32_e32 v0, 2, v126
	v_and_b32_e32 v0, 0xf0, v0
	v_lshl_or_b32 v0, v128, 8, v0
	v_mov_b32_e32 v118, v160
	v_mov_b32_e32 v119, v161
	v_mov_b32_e32 v120, v162
	v_mov_b32_e32 v121, v163
	v_pk_mul_f32 v[134:135], v[114:115], v[118:119] op_sel:[1,1] op_sel_hi:[0,1]
	v_mul_f32_e32 v0, v117, v121
	v_pk_mul_f32 v[144:145], v[114:115], v[118:119] op_sel_hi:[1,0]
	v_pk_fma_f32 v[114:115], v[114:115], v[118:119], v[134:135] op_sel_hi:[1,0,1]
	v_pk_fma_f32 v[118:119], v[116:117], v[120:121], v[0:1] op_sel_hi:[1,1,0] neg_lo:[0,0,1] neg_hi:[0,0,1]
	v_mul_f32_e32 v0, v116, v121
	v_pk_fma_f32 v[116:117], v[116:117], v[120:121], v[0:1] op_sel:[1,0,0] op_sel_hi:[0,1,0]
	v_sub_f32_e32 v114, v144, v134
	v_mov_b32_e32 v117, v116
	v_mov_b32_e32 v116, v118

;   __device__ __forceinline__ void operator()(int m, int n, f32x4 v) const {
;     ...
;     if (n < 256) { v[0] *= 0.125f; v[1] *= 0.125f; v[2] *= 0.125f; v[3] *= 0.125f; }
;     if (m < TX && cd_rope_col(n)) v = rope4(v, rope, key, (n & 63) >> 1);
.LBB0_164:
	s_movk_i32 s6, 0xf0
	v_pk_mul_f32 v[110:111], v[108:109], s[54:55] op_sel_hi:[1,0]
	v_pk_mul_f32 v[112:113], v[106:107], s[54:55] op_sel_hi:[1,0]
	v_cmp_gt_u32_e32 vcc, s6, v136
	s_nop 1
	v_cndmask_b32_e32 v107, v107, v113, vcc
	v_cndmask_b32_e32 v106, v106, v112, vcc
	v_cndmask_b32_e32 v109, v109, v111, vcc
	v_cndmask_b32_e32 v108, v108, v110, vcc
	s_and_saveexec_b64 s[8:9], s[18:19]
	s_cbranch_execz .LBB0_168
	s_cmpk_eq_i32 s51, 0x300
	s_cselect_b64 s[6:7], -1, 0
	s_cmpk_eq_i32 s51, 0x400
	s_cselect_b64 s[10:11], -1, 0
	s_or_b64 s[6:7], s[6:7], s[10:11]
	s_movk_i32 s10, 0x6ef
	s_or_b64 s[6:7], s[6:7], vcc
	v_cmp_lt_u32_e32 vcc, s10, v136
	s_or_b64 s[6:7], s[6:7], vcc
	s_and_saveexec_b64 s[10:11], s[6:7]
	s_cbranch_execz .LBB0_167
	v_lshlrev_b32_e32 v0, 2, v126
	v_and_b32_e32 v0, 0xf0, v0
	v_lshl_or_b32 v0, v118, 8, v0
	v_mov_b32_e32 v110, v168
	v_mov_b32_e32 v111, v169
	v_mov_b32_e32 v112, v170
	v_mov_b32_e32 v113, v171
	v_pk_mul_f32 v[120:121], v[106:107], v[110:111] op_sel:[1,1] op_sel_hi:[0,1]
	v_mul_f32_e32 v0, v109, v113
	v_pk_mul_f32 v[134:135], v[106:107], v[110:111] op_sel_hi:[1,0]
	v_pk_fma_f32 v[106:107], v[106:107], v[110:111], v[120:121] op_sel_hi:[1,0,1]
	v_pk_fma_f32 v[110:111], v[108:109], v[112:113], v[0:1] op_sel_hi:[1,1,0] neg_lo:[0,0,1] neg_hi:[0,0,1]
	v_mul_f32_e32 v0, v108, v113
	v_pk_fma_f32 v[108:109], v[108:109], v[112:113], v[0:1] op_sel:[1,0,0] op_sel_hi:[0,1,0]
	v_sub_f32_e32 v106, v134, v120
	v_mov_b32_e32 v109, v108
	v_mov_b32_e32 v108, v110

;   __device__ __forceinline__ void operator()(int m, int n, f32x4 v) const {
;     ...
;     if (n < 256) { v[0] *= 0.125f; v[1] *= 0.125f; v[2] *= 0.125f; v[3] *= 0.125f; }
;     if (m < TX && cd_rope_col(n)) v = rope4(v, rope, key, (n & 63) >> 1);
.LBB0_170:
	s_movk_i32 s6, 0xf0
	v_pk_mul_f32 v[102:103], v[100:101], s[54:55] op_sel_hi:[1,0]
	v_pk_mul_f32 v[104:105], v[98:99], s[54:55] op_sel_hi:[1,0]
	v_cmp_gt_u32_e32 vcc, s6, v136
	s_nop 1
	v_cndmask_b32_e32 v99, v99, v105, vcc
	v_cndmask_b32_e32 v98, v98, v104, vcc
	v_cndmask_b32_e32 v101, v101, v103, vcc
	v_cndmask_b32_e32 v100, v100, v102, vcc
	s_and_saveexec_b64 s[8:9], s[16:17]
	s_cbranch_execz .LBB0_174
	s_cmpk_eq_i32 s51, 0x300
	s_cselect_b64 s[6:7], -1, 0
	s_cmpk_eq_i32 s51, 0x400
	s_cselect_b64 s[10:11], -1, 0
	s_or_b64 s[6:7], s[6:7], s[10:11]
	s_movk_i32 s10, 0x6ef
	s_or_b64 s[6:7], s[6:7], vcc
	v_cmp_lt_u32_e32 vcc, s10, v136
	s_or_b64 s[6:7], s[6:7], vcc
	s_and_saveexec_b64 s[10:11], s[6:7]
	s_cbranch_execz .LBB0_173
	v_lshlrev_b32_e32 v0, 2, v126
	v_and_b32_e32 v0, 0xf0, v0
	v_lshl_or_b32 v0, v110, 8, v0
	v_mov_b32_e32 v102, v176
	v_mov_b32_e32 v103, v177
	v_mov_b32_e32 v104, v178
	v_mov_b32_e32 v105, v179
	v_pk_mul_f32 v[112:113], v[98:99], v[102:103] op_sel:[1,1] op_sel_hi:[0,1]
	v_mul_f32_e32 v0, v101, v105
	v_pk_mul_f32 v[120:121], v[98:99], v[102:103] op_sel_hi:[1,0]
	v_pk_fma_f32 v[98:99], v[98:99], v[102:103], v[112:113] op_sel_hi:[1,0,1]
	v_pk_fma_f32 v[102:103], v[100:101], v[104:105], v[0:1] op_sel_hi:[1,1,0] neg_lo:[0,0,1] neg_hi:[0,0,1]
	v_mul_f32_e32 v0, v100, v105
	v_pk_fma_f32 v[100:101], v[100:101], v[104:105], v[0:1] op_sel:[1,0,0] op_sel_hi:[0,1,0]
	v_sub_f32_e32 v98, v120, v112
	v_mov_b32_e32 v101, v100
	v_mov_b32_e32 v100, v102

.LBB0_177:
	s_and_b64 vcc, exec, s[72:73]
	s_cbranch_vccz .LBB0_179
	v_lshlrev_b32_e32 v0, 3, v137
	v_lshl_or_b32 v0, v141, 8, v0
	v_mov_b32_e32 v100, v148
	v_mov_b32_e32 v101, v149
	v_mov_b32_e32 v102, v150
	v_mov_b32_e32 v103, v151
	v_pk_mul_f32 v[104:105], v[94:95], v[100:101] op_sel:[1,1] op_sel_hi:[0,1]
	v_mul_f32_e32 v0, v97, v103
	v_pk_mul_f32 v[112:113], v[94:95], v[100:101] op_sel_hi:[1,0]
	v_pk_fma_f32 v[94:95], v[94:95], v[100:101], v[104:105] op_sel_hi:[1,0,1]
	v_pk_fma_f32 v[100:101], v[96:97], v[102:103], v[0:1] op_sel_hi:[1,1,0] neg_lo:[0,0,1] neg_hi:[0,0,1]
	v_mul_f32_e32 v0, v96, v103
	v_pk_fma_f32 v[96:97], v[96:97], v[102:103], v[0:1] op_sel:[1,0,0] op_sel_hi:[0,1,0]
	v_sub_f32_e32 v94, v112, v104
	v_mov_b32_e32 v97, v96
	v_mov_b32_e32 v96, v100

;   __device__ __forceinline__ void operator()(int m, int n, f32x4 v) const {
;     ...
;     if (n < 256) { v[0] *= 0.125f; v[1] *= 0.125f; v[2] *= 0.125f; v[3] *= 0.125f; }
;     if (m < TX && cd_rope_col(n)) v = rope4(v, rope, key, (n & 63) >> 1);
.LBB0_200:
	s_or_b64 exec, exec, s[0:1]
	v_add_u32_e32 v68, 0x80, v139
	s_mov_b32 s0, 0xff80
	v_cmp_gt_i32_e64 s[22:23], s0, v139
	v_and_b32_e32 v70, 0x7cf, v68
	v_mad_i64_i32 v[66:67], s[0:1], v68, s26, 0
	s_and_saveexec_b64 s[0:1], s[12:13]
	s_xor_b64 s[0:1], exec, s[0:1]
	s_cbranch_execz .LBB0_205
	s_cmp_lt_u32 s47, 4
	v_pk_mul_f32 v[72:73], v[64:65], s[54:55] op_sel_hi:[1,0]
	v_pk_mul_f32 v[74:75], v[62:63], s[54:55] op_sel_hi:[1,0]
	s_cselect_b64 vcc, -1, 0
	v_cndmask_b32_e32 v63, v63, v75, vcc
	v_cndmask_b32_e32 v62, v62, v74, vcc
	v_cndmask_b32_e32 v65, v65, v73, vcc
	v_cndmask_b32_e32 v64, v64, v72, vcc
	s_and_saveexec_b64 s[16:17], s[22:23]
	s_cbranch_execz .LBB0_204
	s_cmpk_eq_i32 s51, 0x300
	s_cselect_b64 s[6:7], -1, 0
	s_cmpk_eq_i32 s51, 0x400
	s_cselect_b64 s[18:19], -1, 0
	s_or_b64 s[6:7], s[6:7], s[18:19]
	s_or_b64 s[6:7], vcc, s[6:7]
	s_and_b32 s18, s47, 0xffff
	s_cmp_gt_u32 s18, 27
	s_cselect_b64 s[18:19], -1, 0
	s_or_b64 s[6:7], s[6:7], s[18:19]
	s_andn2_b64 vcc, exec, s[6:7]
	s_cbranch_vccnz .LBB0_204
	v_lshlrev_b32_e32 v0, 3, v137
	v_lshl_or_b32 v0, v70, 8, v0
	v_mov_b32_e32 v72, v180
	v_mov_b32_e32 v73, v181
	v_mov_b32_e32 v74, v182
	v_mov_b32_e32 v75, v183
	v_pk_mul_f32 v[76:77], v[62:63], v[72:73] op_sel:[1,1] op_sel_hi:[0,1]
	v_mul_f32_e32 v0, v65, v75
	v_pk_mul_f32 v[78:79], v[62:63], v[72:73] op_sel_hi:[1,0]
	v_pk_fma_f32 v[62:63], v[62:63], v[72:73], v[76:77] op_sel_hi:[1,0,1]
	v_pk_fma_f32 v[72:73], v[64:65], v[74:75], v[0:1] op_sel_hi:[1,1,0] neg_lo:[0,0,1] neg_hi:[0,0,1]
	v_mul_f32_e32 v0, v64, v75
	v_pk_fma_f32 v[64:65], v[64:65], v[74:75], v[0:1] op_sel:[1,0,0] op_sel_hi:[0,1,0]
	v_sub_f32_e32 v62, v78, v76
	v_mov_b32_e32 v65, v64
	v_mov_b32_e32 v64, v72

;   __device__ __forceinline__ void operator()(int m, int n, f32x4 v) const {
;     ...
;     if (n < 256) { v[0] *= 0.125f; v[1] *= 0.125f; v[2] *= 0.125f; v[3] *= 0.125f; }
;     if (m < TX && cd_rope_col(n)) v = rope4(v, rope, key, (n & 63) >> 1);
.LBB0_209:
	s_or_b64 exec, exec, s[0:1]
	v_add_u32_e32 v60, 0x90, v139
	s_mov_b32 s0, 0xff70
	v_cmp_gt_i32_e64 s[20:21], s0, v139
	v_and_b32_e32 v62, 0x7df, v60
	v_mad_i64_i32 v[58:59], s[0:1], v60, s26, 0
	s_and_saveexec_b64 s[0:1], s[12:13]
	s_xor_b64 s[0:1], exec, s[0:1]
	s_cbranch_execz .LBB0_214
	s_cmp_lt_u32 s47, 4
	v_pk_mul_f32 v[64:65], v[56:57], s[54:55] op_sel_hi:[1,0]
	v_pk_mul_f32 v[72:73], v[54:55], s[54:55] op_sel_hi:[1,0]
	s_cselect_b64 vcc, -1, 0
	v_cndmask_b32_e32 v55, v55, v73, vcc
	v_cndmask_b32_e32 v54, v54, v72, vcc
	v_cndmask_b32_e32 v57, v57, v65, vcc
	v_cndmask_b32_e32 v56, v56, v64, vcc
	s_and_saveexec_b64 s[16:17], s[20:21]
	s_cbranch_execz .LBB0_213
	s_cmpk_eq_i32 s51, 0x300
	s_cselect_b64 s[6:7], -1, 0
	s_cmpk_eq_i32 s51, 0x400
	s_cselect_b64 s[18:19], -1, 0
	s_or_b64 s[6:7], s[6:7], s[18:19]
	s_or_b64 s[6:7], vcc, s[6:7]
	s_and_b32 s18, s47, 0xffff
	s_cmp_gt_u32 s18, 27
	s_cselect_b64 s[18:19], -1, 0
	s_or_b64 s[6:7], s[6:7], s[18:19]
	s_andn2_b64 vcc, exec, s[6:7]
	s_cbranch_vccnz .LBB0_213
	v_lshlrev_b32_e32 v0, 3, v137
	v_lshl_or_b32 v0, v62, 8, v0
	v_mov_b32_e32 v72, v188
	v_mov_b32_e32 v73, v189
	v_mov_b32_e32 v74, v190
	v_mov_b32_e32 v75, v191
	v_pk_mul_f32 v[64:65], v[54:55], v[72:73] op_sel:[1,1] op_sel_hi:[0,1]
	v_mul_f32_e32 v0, v57, v75
	v_pk_mul_f32 v[76:77], v[54:55], v[72:73] op_sel_hi:[1,0]
	v_pk_fma_f32 v[54:55], v[54:55], v[72:73], v[64:65] op_sel_hi:[1,0,1]
	v_pk_fma_f32 v[72:73], v[56:57], v[74:75], v[0:1] op_sel_hi:[1,1,0] neg_lo:[0,0,1] neg_hi:[0,0,1]
	v_mul_f32_e32 v0, v56, v75
	v_pk_fma_f32 v[56:57], v[56:57], v[74:75], v[0:1] op_sel:[1,0,0] op_sel_hi:[0,1,0]
	v_sub_f32_e32 v54, v76, v64
	v_mov_b32_e32 v57, v56
	v_mov_b32_e32 v56, v72

;   __device__ __forceinline__ void operator()(int m, int n, f32x4 v) const {
;     ...
;     if (n < 256) { v[0] *= 0.125f; v[1] *= 0.125f; v[2] *= 0.125f; v[3] *= 0.125f; }
;     if (m < TX && cd_rope_col(n)) v = rope4(v, rope, key, (n & 63) >> 1);
.LBB0_218:
	s_or_b64 exec, exec, s[0:1]
	v_add_u32_e32 v52, 0xa0, v139
	s_mov_b32 s0, 0xff60
	v_cmp_gt_i32_e64 s[18:19], s0, v139
	v_and_b32_e32 v54, 0x7ef, v52
	v_mad_i64_i32 v[50:51], s[0:1], v52, s26, 0
	s_and_saveexec_b64 s[0:1], s[12:13]
	s_xor_b64 s[0:1], exec, s[0:1]
	s_cbranch_execz .LBB0_223
	s_cmp_lt_u32 s47, 4
	v_pk_mul_f32 v[56:57], v[48:49], s[54:55] op_sel_hi:[1,0]
	v_pk_mul_f32 v[64:65], v[46:47], s[54:55] op_sel_hi:[1,0]
	s_cselect_b64 vcc, -1, 0
	v_cndmask_b32_e32 v47, v47, v65, vcc
	v_cndmask_b32_e32 v46, v46, v64, vcc
	v_cndmask_b32_e32 v49, v49, v57, vcc
	v_cndmask_b32_e32 v48, v48, v56, vcc
	s_and_saveexec_b64 s[16:17], s[18:19]
	s_cbranch_execz .LBB0_222
	s_cmpk_eq_i32 s51, 0x300
	s_cselect_b64 s[6:7], -1, 0
	s_cmpk_eq_i32 s51, 0x400
	s_cselect_b64 s[66:67], -1, 0
	s_or_b64 s[6:7], s[6:7], s[66:67]
	s_or_b64 s[6:7], vcc, s[6:7]
	s_and_b32 s34, s47, 0xffff
	s_cmp_gt_u32 s34, 27
	s_cselect_b64 s[66:67], -1, 0
	s_or_b64 s[6:7], s[6:7], s[66:67]
	s_andn2_b64 vcc, exec, s[6:7]
	s_cbranch_vccnz .LBB0_222
	v_lshlrev_b32_e32 v0, 3, v137
	v_lshl_or_b32 v0, v54, 8, v0
	v_mov_b32_e32 v72, v208
	v_mov_b32_e32 v73, v209
	v_mov_b32_e32 v74, v210
	v_mov_b32_e32 v75, v211
	v_pk_mul_f32 v[56:57], v[46:47], v[72:73] op_sel:[1,1] op_sel_hi:[0,1]
	v_mul_f32_e32 v0, v49, v75
	v_pk_mul_f32 v[64:65], v[46:47], v[72:73] op_sel_hi:[1,0]
	v_pk_fma_f32 v[46:47], v[46:47], v[72:73], v[56:57] op_sel_hi:[1,0,1]
	v_pk_fma_f32 v[72:73], v[48:49], v[74:75], v[0:1] op_sel_hi:[1,1,0] neg_lo:[0,0,1] neg_hi:[0,0,1]
	v_mul_f32_e32 v0, v48, v75
	v_pk_fma_f32 v[48:49], v[48:49], v[74:75], v[0:1] op_sel:[1,0,0] op_sel_hi:[0,1,0]
	v_sub_f32_e32 v46, v64, v56
	v_mov_b32_e32 v49, v48
	v_mov_b32_e32 v48, v72

;   __device__ __forceinline__ void operator()(int m, int n, f32x4 v) const {
;     ...
;     if (n < 256) { v[0] *= 0.125f; v[1] *= 0.125f; v[2] *= 0.125f; v[3] *= 0.125f; }
;     if (m < TX && cd_rope_col(n)) v = rope4(v, rope, key, (n & 63) >> 1);
.LBB0_227:
	s_or_b64 exec, exec, s[0:1]
	v_add_u32_e32 v44, 0xb0, v139
	s_mov_b32 s0, 0xff50
	v_cmp_gt_i32_e64 s[16:17], s0, v139
	v_and_b32_e32 v46, 0x7ff, v44
	v_mad_i64_i32 v[42:43], s[0:1], v44, s26, 0
	s_and_saveexec_b64 s[0:1], s[12:13]
	s_xor_b64 s[0:1], exec, s[0:1]
	s_cbranch_execz .LBB0_232
	s_cmp_lt_u32 s47, 4
	v_pk_mul_f32 v[48:49], v[40:41], s[54:55] op_sel_hi:[1,0]
	v_pk_mul_f32 v[56:57], v[38:39], s[54:55] op_sel_hi:[1,0]
	s_cselect_b64 vcc, -1, 0
	v_cndmask_b32_e32 v39, v39, v57, vcc
	v_cndmask_b32_e32 v38, v38, v56, vcc
	v_cndmask_b32_e32 v41, v41, v49, vcc
	v_cndmask_b32_e32 v40, v40, v48, vcc
	s_and_saveexec_b64 s[12:13], s[16:17]
	s_cbranch_execz .LBB0_231
	s_cmpk_eq_i32 s51, 0x300
	s_cselect_b64 s[6:7], -1, 0
	s_cmpk_eq_i32 s51, 0x400
	s_cselect_b64 s[66:67], -1, 0
	s_or_b64 s[6:7], s[6:7], s[66:67]
	s_or_b64 s[6:7], vcc, s[6:7]
	s_and_b32 s34, s47, 0xffff
	s_cmp_gt_u32 s34, 27
	s_cselect_b64 s[46:47], -1, 0
	s_or_b64 s[6:7], s[6:7], s[46:47]
	s_andn2_b64 vcc, exec, s[6:7]
	s_cbranch_vccnz .LBB0_231
	v_lshlrev_b32_e32 v0, 3, v137
	v_lshl_or_b32 v0, v46, 8, v0
	v_mov_b32_e32 v72, v216
	v_mov_b32_e32 v73, v217
	v_mov_b32_e32 v74, v218
	v_mov_b32_e32 v75, v219
	v_mul_f32_e32 v0, v41, v75
	v_pk_mul_f32 v[48:49], v[38:39], v[72:73] op_sel:[1,1] op_sel_hi:[0,1]
	v_pk_fma_f32 v[64:65], v[40:41], v[74:75], v[0:1] op_sel_hi:[1,1,0] neg_lo:[0,0,1] neg_hi:[0,0,1]
	v_mul_f32_e32 v0, v40, v75
	v_pk_mul_f32 v[56:57], v[38:39], v[72:73] op_sel_hi:[1,0]
	v_pk_fma_f32 v[38:39], v[38:39], v[72:73], v[48:49] op_sel_hi:[1,0,1]
	v_pk_fma_f32 v[40:41], v[40:41], v[74:75], v[0:1] op_sel:[1,0,0] op_sel_hi:[0,1,0]
	v_sub_f32_e32 v38, v56, v48
	v_mov_b32_e32 v41, v40
	v_mov_b32_e32 v40, v64

;   __device__ __forceinline__ void operator()(int m, int n, f32x4 v) const {
;     ...
;     if (n < 256) { v[0] *= 0.125f; v[1] *= 0.125f; v[2] *= 0.125f; v[3] *= 0.125f; }
;     if (m < TX && cd_rope_col(n)) v = rope4(v, rope, key, (n & 63) >> 1);
.LBB0_251:
	s_movk_i32 s0, 0x380
	v_cmp_ne_u32_e32 vcc, s0, v95
	s_and_saveexec_b64 s[0:1], vcc
	s_xor_b64 s[0:1], exec, s[0:1]
	s_cbranch_execz .LBB0_257
	s_movk_i32 s6, 0x70
	v_pk_mul_f32 v[100:101], v[92:93], s[54:55] op_sel_hi:[1,0]
	v_pk_mul_f32 v[102:103], v[90:91], s[54:55] op_sel_hi:[1,0]
	v_cmp_gt_u32_e32 vcc, s6, v136
	s_nop 1
	v_cndmask_b32_e32 v91, v91, v103, vcc
	v_cndmask_b32_e32 v90, v90, v102, vcc
	v_cndmask_b32_e32 v93, v93, v101, vcc
	v_cndmask_b32_e32 v92, v92, v100, vcc
	s_and_saveexec_b64 s[72:73], s[22:23]
	s_cbranch_execz .LBB0_256
	s_cmpk_eq_i32 s51, 0x400
	s_cselect_b64 s[6:7], -1, 0
	s_movk_i32 s22, 0x66f
	s_or_b64 s[6:7], s[6:7], vcc
	v_cmp_lt_u32_e32 vcc, s22, v136
	s_or_b64 s[6:7], s[6:7], vcc
	s_and_saveexec_b64 s[22:23], s[6:7]
	s_cbranch_execz .LBB0_255
	v_lshlrev_b32_e32 v0, 2, v94
	v_and_b32_e32 v0, 0xf0, v0
	v_lshl_or_b32 v0, v141, 8, v0
	v_mov_b32_e32 v100, v152
	v_mov_b32_e32 v101, v153
	v_mov_b32_e32 v102, v154
	v_mov_b32_e32 v103, v155
	v_pk_mul_f32 v[104:105], v[90:91], v[100:101] op_sel:[1,1] op_sel_hi:[0,1]
	v_mul_f32_e32 v0, v93, v103
	v_pk_mul_f32 v[112:113], v[90:91], v[100:101] op_sel_hi:[1,0]
	v_pk_fma_f32 v[90:91], v[90:91], v[100:101], v[104:105] op_sel_hi:[1,0,1]
	v_pk_fma_f32 v[100:101], v[92:93], v[102:103], v[0:1] op_sel_hi:[1,1,0] neg_lo:[0,0,1] neg_hi:[0,0,1]
	v_mul_f32_e32 v0, v92, v103
	v_pk_fma_f32 v[92:93], v[92:93], v[102:103], v[0:1] op_sel:[1,0,0] op_sel_hi:[0,1,0]
	v_sub_f32_e32 v90, v112, v104
	v_mov_b32_e32 v93, v92
	v_mov_b32_e32 v92, v100

;   __device__ __forceinline__ void operator()(int m, int n, f32x4 v) const {
;     ...
;     if (n < 256) { v[0] *= 0.125f; v[1] *= 0.125f; v[2] *= 0.125f; v[3] *= 0.125f; }
;     if (m < TX && cd_rope_col(n)) v = rope4(v, rope, key, (n & 63) >> 1);
.LBB0_267:
	s_movk_i32 s6, 0xf0
	v_pk_mul_f32 v[62:63], v[60:61], s[54:55] op_sel_hi:[1,0]
	v_pk_mul_f32 v[64:65], v[58:59], s[54:55] op_sel_hi:[1,0]
	v_cmp_gt_u32_e32 vcc, s6, v136
	s_nop 1
	v_cndmask_b32_e32 v59, v59, v65, vcc
	v_cndmask_b32_e32 v58, v58, v64, vcc
	v_cndmask_b32_e32 v61, v61, v63, vcc
	v_cndmask_b32_e32 v60, v60, v62, vcc
	s_and_saveexec_b64 s[16:17], s[22:23]
	s_cbranch_execz .LBB0_271
	s_cmpk_eq_i32 s51, 0x300
	s_cselect_b64 s[6:7], -1, 0
	s_cmpk_eq_i32 s51, 0x400
	s_cselect_b64 s[18:19], -1, 0
	s_or_b64 s[6:7], s[6:7], s[18:19]
	s_movk_i32 s18, 0x6ef
	s_or_b64 s[6:7], s[6:7], vcc
	v_cmp_lt_u32_e32 vcc, s18, v136
	s_or_b64 s[6:7], s[6:7], vcc
	s_and_saveexec_b64 s[18:19], s[6:7]
	s_cbranch_execz .LBB0_270
	v_lshlrev_b32_e32 v0, 2, v126
	v_and_b32_e32 v0, 0xf0, v0
	v_lshl_or_b32 v0, v70, 8, v0
	v_mov_b32_e32 v62, v184
	v_mov_b32_e32 v63, v185
	v_mov_b32_e32 v64, v186
	v_mov_b32_e32 v65, v187
	v_pk_mul_f32 v[72:73], v[58:59], v[62:63] op_sel:[1,1] op_sel_hi:[0,1]
	v_mul_f32_e32 v0, v61, v65
	v_pk_mul_f32 v[74:75], v[58:59], v[62:63] op_sel_hi:[1,0]
	v_pk_fma_f32 v[58:59], v[58:59], v[62:63], v[72:73] op_sel_hi:[1,0,1]
	v_pk_fma_f32 v[62:63], v[60:61], v[64:65], v[0:1] op_sel_hi:[1,1,0] neg_lo:[0,0,1] neg_hi:[0,0,1]
	v_mul_f32_e32 v0, v60, v65
	v_pk_fma_f32 v[60:61], v[60:61], v[64:65], v[0:1] op_sel:[1,0,0] op_sel_hi:[0,1,0]
	v_sub_f32_e32 v58, v74, v72
	v_mov_b32_e32 v61, v60
	v_mov_b32_e32 v60, v62

;   __device__ __forceinline__ void operator()(int m, int n, f32x4 v) const {
;     ...
;     if (n < 256) { v[0] *= 0.125f; v[1] *= 0.125f; v[2] *= 0.125f; v[3] *= 0.125f; }
;     if (m < TX && cd_rope_col(n)) v = rope4(v, rope, key, (n & 63) >> 1);
.LBB0_273:
	s_movk_i32 s6, 0xf0
	v_pk_mul_f32 v[54:55], v[52:53], s[54:55] op_sel_hi:[1,0]
	v_pk_mul_f32 v[56:57], v[50:51], s[54:55] op_sel_hi:[1,0]
	v_cmp_gt_u32_e32 vcc, s6, v136
	s_nop 1
	v_cndmask_b32_e32 v51, v51, v57, vcc
	v_cndmask_b32_e32 v50, v50, v56, vcc
	v_cndmask_b32_e32 v53, v53, v55, vcc
	v_cndmask_b32_e32 v52, v52, v54, vcc
	s_and_saveexec_b64 s[16:17], s[20:21]
	s_cbranch_execz .LBB0_277
	s_cmpk_eq_i32 s51, 0x300
	s_cselect_b64 s[6:7], -1, 0
	s_cmpk_eq_i32 s51, 0x400
	s_cselect_b64 s[18:19], -1, 0
	s_or_b64 s[6:7], s[6:7], s[18:19]
	s_movk_i32 s18, 0x6ef
	s_or_b64 s[6:7], s[6:7], vcc
	v_cmp_lt_u32_e32 vcc, s18, v136
	s_or_b64 s[6:7], s[6:7], vcc
	s_and_saveexec_b64 s[18:19], s[6:7]
	s_cbranch_execz .LBB0_276
	v_lshlrev_b32_e32 v0, 2, v126
	v_and_b32_e32 v0, 0xf0, v0
	v_lshl_or_b32 v0, v62, 8, v0
	v_mov_b32_e32 v54, v192
	v_mov_b32_e32 v55, v193
	v_mov_b32_e32 v56, v194
	v_mov_b32_e32 v57, v195
	v_pk_mul_f32 v[64:65], v[50:51], v[54:55] op_sel:[1,1] op_sel_hi:[0,1]
	v_mul_f32_e32 v0, v53, v57
	v_pk_mul_f32 v[72:73], v[50:51], v[54:55] op_sel_hi:[1,0]
	v_pk_fma_f32 v[50:51], v[50:51], v[54:55], v[64:65] op_sel_hi:[1,0,1]
	v_pk_fma_f32 v[54:55], v[52:53], v[56:57], v[0:1] op_sel_hi:[1,1,0] neg_lo:[0,0,1] neg_hi:[0,0,1]
	v_mul_f32_e32 v0, v52, v57
	v_pk_fma_f32 v[52:53], v[52:53], v[56:57], v[0:1] op_sel:[1,0,0] op_sel_hi:[0,1,0]
	v_sub_f32_e32 v50, v72, v64
	v_mov_b32_e32 v53, v52
	v_mov_b32_e32 v52, v54

;   __device__ __forceinline__ void operator()(int m, int n, f32x4 v) const {
;     ...
;     if (n < 256) { v[0] *= 0.125f; v[1] *= 0.125f; v[2] *= 0.125f; v[3] *= 0.125f; }
;     if (m < TX && cd_rope_col(n)) v = rope4(v, rope, key, (n & 63) >> 1);
.LBB0_279:
	s_movk_i32 s6, 0xf0
	v_pk_mul_f32 v[46:47], v[44:45], s[54:55] op_sel_hi:[1,0]
	v_pk_mul_f32 v[48:49], v[42:43], s[54:55] op_sel_hi:[1,0]
	v_cmp_gt_u32_e32 vcc, s6, v136
	s_nop 1
	v_cndmask_b32_e32 v43, v43, v49, vcc
	v_cndmask_b32_e32 v42, v42, v48, vcc
	v_cndmask_b32_e32 v45, v45, v47, vcc
	v_cndmask_b32_e32 v44, v44, v46, vcc
	s_and_saveexec_b64 s[16:17], s[18:19]
	s_cbranch_execz .LBB0_283
	s_cmpk_eq_i32 s51, 0x300
	s_cselect_b64 s[6:7], -1, 0
	s_cmpk_eq_i32 s51, 0x400
	s_cselect_b64 s[66:67], -1, 0
	s_or_b64 s[6:7], s[6:7], s[66:67]
	s_movk_i32 s34, 0x6ef
	s_or_b64 s[6:7], s[6:7], vcc
	v_cmp_lt_u32_e32 vcc, s34, v136
	s_or_b64 s[6:7], s[6:7], vcc
	s_and_saveexec_b64 s[66:67], s[6:7]
	s_cbranch_execz .LBB0_282
	v_lshlrev_b32_e32 v0, 2, v126
	v_and_b32_e32 v0, 0xf0, v0
	v_lshl_or_b32 v0, v54, 8, v0
	v_mov_b32_e32 v46, v212
	v_mov_b32_e32 v47, v213
	v_mov_b32_e32 v48, v214
	v_mov_b32_e32 v49, v215
	v_pk_mul_f32 v[56:57], v[42:43], v[46:47] op_sel:[1,1] op_sel_hi:[0,1]
	v_mul_f32_e32 v0, v45, v49
	v_pk_mul_f32 v[64:65], v[42:43], v[46:47] op_sel_hi:[1,0]
	v_pk_fma_f32 v[42:43], v[42:43], v[46:47], v[56:57] op_sel_hi:[1,0,1]
	v_pk_fma_f32 v[46:47], v[44:45], v[48:49], v[0:1] op_sel_hi:[1,1,0] neg_lo:[0,0,1] neg_hi:[0,0,1]
	v_mul_f32_e32 v0, v44, v49
	v_pk_fma_f32 v[44:45], v[44:45], v[48:49], v[0:1] op_sel:[1,0,0] op_sel_hi:[0,1,0]
	v_sub_f32_e32 v42, v64, v56
	v_mov_b32_e32 v45, v44
	v_mov_b32_e32 v44, v46

;   __device__ __forceinline__ void operator()(int m, int n, f32x4 v) const {
;     ...
;     if (n < 256) { v[0] *= 0.125f; v[1] *= 0.125f; v[2] *= 0.125f; v[3] *= 0.125f; }
;     if (m < TX && cd_rope_col(n)) v = rope4(v, rope, key, (n & 63) >> 1);
.LBB0_285:
	s_movk_i32 s6, 0xf0
	v_pk_mul_f32 v[38:39], v[36:37], s[54:55] op_sel_hi:[1,0]
	v_pk_mul_f32 v[40:41], v[34:35], s[54:55] op_sel_hi:[1,0]
	v_cmp_gt_u32_e32 vcc, s6, v136
	s_nop 1
	v_cndmask_b32_e32 v35, v35, v41, vcc
	v_cndmask_b32_e32 v34, v34, v40, vcc
	v_cndmask_b32_e32 v37, v37, v39, vcc
	v_cndmask_b32_e32 v36, v36, v38, vcc
	s_and_saveexec_b64 s[12:13], s[16:17]
	s_cbranch_execz .LBB0_289
	s_cmpk_eq_i32 s51, 0x300
	s_cselect_b64 s[6:7], -1, 0
	s_cmpk_eq_i32 s51, 0x400
	s_cselect_b64 s[14:15], -1, 0
	s_or_b64 s[6:7], s[6:7], s[14:15]
	s_movk_i32 s14, 0x6ef
	s_or_b64 s[6:7], s[6:7], vcc
	v_cmp_lt_u32_e32 vcc, s14, v136
	s_or_b64 s[6:7], s[6:7], vcc
	s_and_saveexec_b64 s[14:15], s[6:7]
	s_cbranch_execz .LBB0_288
	v_lshlrev_b32_e32 v0, 2, v126
	v_and_b32_e32 v0, 0xf0, v0
	v_lshl_or_b32 v0, v46, 8, v0
	v_mov_b32_e32 v38, v220
	v_mov_b32_e32 v39, v221
	v_mov_b32_e32 v40, v222
	v_mov_b32_e32 v41, v223
	v_pk_mul_f32 v[48:49], v[34:35], v[38:39] op_sel:[1,1] op_sel_hi:[0,1]
	v_mul_f32_e32 v0, v37, v41
	v_pk_mul_f32 v[56:57], v[34:35], v[38:39] op_sel_hi:[1,0]
	v_pk_fma_f32 v[34:35], v[34:35], v[38:39], v[48:49] op_sel_hi:[1,0,1]
	v_pk_fma_f32 v[38:39], v[36:37], v[40:41], v[0:1] op_sel_hi:[1,1,0] neg_lo:[0,0,1] neg_hi:[0,0,1]
	v_mul_f32_e32 v0, v36, v41
	v_pk_fma_f32 v[36:37], v[36:37], v[40:41], v[0:1] op_sel:[1,0,0] op_sel_hi:[0,1,0]
	v_sub_f32_e32 v34, v56, v48
	v_mov_b32_e32 v37, v36
	v_mov_b32_e32 v36, v38

.LBB0_298:
	s_and_b64 vcc, exec, s[72:73]
	s_cbranch_vccz .LBB0_300
	v_lshlrev_b32_e32 v0, 3, v137
	v_lshl_or_b32 v0, v128, 8, v0
	v_mov_b32_e32 v90, v156
	v_mov_b32_e32 v91, v157
	v_mov_b32_e32 v92, v158
	v_mov_b32_e32 v93, v159
	v_pk_mul_f32 v[100:101], v[86:87], v[90:91] op_sel:[1,1] op_sel_hi:[0,1]
	v_mul_f32_e32 v0, v89, v93
	v_pk_mul_f32 v[102:103], v[86:87], v[90:91] op_sel_hi:[1,0]
	v_pk_fma_f32 v[86:87], v[86:87], v[90:91], v[100:101] op_sel_hi:[1,0,1]
	v_pk_fma_f32 v[90:91], v[88:89], v[92:93], v[0:1] op_sel_hi:[1,1,0] neg_lo:[0,0,1] neg_hi:[0,0,1]
	v_mul_f32_e32 v0, v88, v93
	v_pk_fma_f32 v[88:89], v[88:89], v[92:93], v[0:1] op_sel:[1,0,0] op_sel_hi:[0,1,0]
	v_sub_f32_e32 v86, v102, v100
	v_mov_b32_e32 v89, v88
	v_mov_b32_e32 v88, v90

;   __device__ __forceinline__ void operator()(int m, int n, f32x4 v) const {
;     ...
;     if (n < 256) { v[0] *= 0.125f; v[1] *= 0.125f; v[2] *= 0.125f; v[3] *= 0.125f; }
;     if (m < TX && cd_rope_col(n)) v = rope4(v, rope, key, (n & 63) >> 1);
.LBB0_305:
	s_movk_i32 s0, 0x380
	v_cmp_ne_u32_e32 vcc, s0, v95
	s_and_saveexec_b64 s[0:1], vcc
	s_xor_b64 s[0:1], exec, s[0:1]
	s_cbranch_execz .LBB0_311
	s_movk_i32 s6, 0x70
	v_pk_mul_f32 v[86:87], v[84:85], s[54:55] op_sel_hi:[1,0]
	v_pk_mul_f32 v[88:89], v[82:83], s[54:55] op_sel_hi:[1,0]
	v_cmp_gt_u32_e32 vcc, s6, v136
	s_nop 1
	v_cndmask_b32_e32 v83, v83, v89, vcc
	v_cndmask_b32_e32 v82, v82, v88, vcc
	v_cndmask_b32_e32 v85, v85, v87, vcc
	v_cndmask_b32_e32 v84, v84, v86, vcc
	s_and_saveexec_b64 s[66:67], s[20:21]
	s_cbranch_execz .LBB0_310
	s_cmpk_eq_i32 s51, 0x400
	s_cselect_b64 s[6:7], -1, 0
	s_movk_i32 s20, 0x66f
	s_or_b64 s[6:7], s[6:7], vcc
	v_cmp_lt_u32_e32 vcc, s20, v136
	s_or_b64 s[6:7], s[6:7], vcc
	s_and_saveexec_b64 s[20:21], s[6:7]
	s_cbranch_execz .LBB0_309
	v_lshlrev_b32_e32 v0, 2, v94
	v_and_b32_e32 v0, 0xf0, v0
	v_lshl_or_b32 v0, v128, 8, v0
	v_mov_b32_e32 v86, v160
	v_mov_b32_e32 v87, v161
	v_mov_b32_e32 v88, v162
	v_mov_b32_e32 v89, v163
	v_pk_mul_f32 v[90:91], v[82:83], v[86:87] op_sel:[1,1] op_sel_hi:[0,1]
	v_mul_f32_e32 v0, v85, v89
	v_pk_mul_f32 v[92:93], v[82:83], v[86:87] op_sel_hi:[1,0]
	v_pk_fma_f32 v[82:83], v[82:83], v[86:87], v[90:91] op_sel_hi:[1,0,1]
	v_pk_fma_f32 v[86:87], v[84:85], v[88:89], v[0:1] op_sel_hi:[1,1,0] neg_lo:[0,0,1] neg_hi:[0,0,1]
	v_mul_f32_e32 v0, v84, v89
	v_pk_fma_f32 v[84:85], v[84:85], v[88:89], v[0:1] op_sel:[1,0,0] op_sel_hi:[0,1,0]
	v_sub_f32_e32 v82, v92, v90
	v_mov_b32_e32 v85, v84
	v_mov_b32_e32 v84, v86

.LBB0_322:
	s_and_b64 vcc, exec, s[66:67]
	s_cbranch_vccz .LBB0_324
	v_lshlrev_b32_e32 v0, 3, v137
	v_lshl_or_b32 v0, v70, 8, v0
	v_mov_b32_e32 v34, v180
	v_mov_b32_e32 v35, v181
	v_mov_b32_e32 v36, v182
	v_mov_b32_e32 v37, v183
	v_pk_mul_f32 v[38:39], v[30:31], v[34:35] op_sel:[1,1] op_sel_hi:[0,1]
	v_mul_f32_e32 v0, v33, v37
	v_pk_mul_f32 v[40:41], v[30:31], v[34:35] op_sel_hi:[1,0]
	v_pk_fma_f32 v[30:31], v[30:31], v[34:35], v[38:39] op_sel_hi:[1,0,1]
	v_pk_fma_f32 v[34:35], v[32:33], v[36:37], v[0:1] op_sel_hi:[1,1,0] neg_lo:[0,0,1] neg_hi:[0,0,1]
	v_mul_f32_e32 v0, v32, v37
	v_pk_fma_f32 v[32:33], v[32:33], v[36:37], v[0:1] op_sel:[1,0,0] op_sel_hi:[0,1,0]
	v_sub_f32_e32 v30, v40, v38
	v_mov_b32_e32 v33, v32
	v_mov_b32_e32 v32, v34

;   __device__ __forceinline__ void operator()(int m, int n, f32x4 v) const {
;     ...
;     if (n < 256) { v[0] *= 0.125f; v[1] *= 0.125f; v[2] *= 0.125f; v[3] *= 0.125f; }
;     if (m < TX && cd_rope_col(n)) v = rope4(v, rope, key, (n & 63) >> 1);
.LBB0_329:
	s_movk_i32 s0, 0x380
	v_cmp_ne_u32_e32 vcc, s0, v95
	s_and_saveexec_b64 s[0:1], vcc
	s_xor_b64 s[0:1], exec, s[0:1]
	s_cbranch_execz .LBB0_335
	s_movk_i32 s6, 0x70
	v_pk_mul_f32 v[30:31], v[28:29], s[54:55] op_sel_hi:[1,0]
	v_pk_mul_f32 v[32:33], v[26:27], s[54:55] op_sel_hi:[1,0]
	v_cmp_gt_u32_e32 vcc, s6, v136
	s_nop 1
	v_cndmask_b32_e32 v27, v27, v33, vcc
	v_cndmask_b32_e32 v26, v26, v32, vcc
	v_cndmask_b32_e32 v29, v29, v31, vcc
	v_cndmask_b32_e32 v28, v28, v30, vcc
	s_and_saveexec_b64 s[14:15], s[22:23]
	s_cbranch_execz .LBB0_334
	s_cmpk_eq_i32 s51, 0x400
	s_cselect_b64 s[6:7], -1, 0
	s_movk_i32 s22, 0x66f
	s_or_b64 s[6:7], s[6:7], vcc
	v_cmp_lt_u32_e32 vcc, s22, v136
	s_or_b64 s[6:7], s[6:7], vcc
	s_and_saveexec_b64 s[22:23], s[6:7]
	s_cbranch_execz .LBB0_333
	v_lshlrev_b32_e32 v0, 2, v94
	v_and_b32_e32 v0, 0xf0, v0
	v_lshl_or_b32 v0, v70, 8, v0
	v_mov_b32_e32 v30, v184
	v_mov_b32_e32 v31, v185
	v_mov_b32_e32 v32, v186
	v_mov_b32_e32 v33, v187
	v_pk_mul_f32 v[34:35], v[26:27], v[30:31] op_sel:[1,1] op_sel_hi:[0,1]
	v_mul_f32_e32 v0, v29, v33
	v_pk_mul_f32 v[36:37], v[26:27], v[30:31] op_sel_hi:[1,0]
	v_pk_fma_f32 v[26:27], v[26:27], v[30:31], v[34:35] op_sel_hi:[1,0,1]
	v_pk_fma_f32 v[30:31], v[28:29], v[32:33], v[0:1] op_sel_hi:[1,1,0] neg_lo:[0,0,1] neg_hi:[0,0,1]
	v_mul_f32_e32 v0, v28, v33
	v_pk_fma_f32 v[28:29], v[28:29], v[32:33], v[0:1] op_sel:[1,0,0] op_sel_hi:[0,1,0]
	v_sub_f32_e32 v26, v36, v34
	v_mov_b32_e32 v29, v28
	v_mov_b32_e32 v28, v30

.LBB0_346:
	s_and_b64 vcc, exec, s[66:67]
	s_cbranch_vccz .LBB0_348
	v_lshlrev_b32_e32 v0, 3, v137
	v_lshl_or_b32 v0, v118, 8, v0
	v_mov_b32_e32 v82, v164
	v_mov_b32_e32 v83, v165
	v_mov_b32_e32 v84, v166
	v_mov_b32_e32 v85, v167
	v_pk_mul_f32 v[86:87], v[78:79], v[82:83] op_sel:[1,1] op_sel_hi:[0,1]
	v_mul_f32_e32 v0, v81, v85
	v_pk_mul_f32 v[88:89], v[78:79], v[82:83] op_sel_hi:[1,0]
	v_pk_fma_f32 v[78:79], v[78:79], v[82:83], v[86:87] op_sel_hi:[1,0,1]
	v_pk_fma_f32 v[82:83], v[80:81], v[84:85], v[0:1] op_sel_hi:[1,1,0] neg_lo:[0,0,1] neg_hi:[0,0,1]
	v_mul_f32_e32 v0, v80, v85
	v_pk_fma_f32 v[80:81], v[80:81], v[84:85], v[0:1] op_sel:[1,0,0] op_sel_hi:[0,1,0]
	v_sub_f32_e32 v78, v88, v86
	v_mov_b32_e32 v81, v80
	v_mov_b32_e32 v80, v82

;   __device__ __forceinline__ void operator()(int m, int n, f32x4 v) const {
;     ...
;     if (n < 256) { v[0] *= 0.125f; v[1] *= 0.125f; v[2] *= 0.125f; v[3] *= 0.125f; }
;     if (m < TX && cd_rope_col(n)) v = rope4(v, rope, key, (n & 63) >> 1);
.LBB0_353:
	s_movk_i32 s0, 0x380
	v_cmp_ne_u32_e32 vcc, s0, v95
	s_and_saveexec_b64 s[0:1], vcc
	s_xor_b64 s[0:1], exec, s[0:1]
	s_cbranch_execz .LBB0_359
	s_movk_i32 s6, 0x70
	v_pk_mul_f32 v[78:79], v[76:77], s[54:55] op_sel_hi:[1,0]
	v_pk_mul_f32 v[80:81], v[74:75], s[54:55] op_sel_hi:[1,0]
	v_cmp_gt_u32_e32 vcc, s6, v136
	s_nop 1
	v_cndmask_b32_e32 v75, v75, v81, vcc
	v_cndmask_b32_e32 v74, v74, v80, vcc
	v_cndmask_b32_e32 v77, v77, v79, vcc
	v_cndmask_b32_e32 v76, v76, v78, vcc
	s_and_saveexec_b64 s[22:23], s[18:19]
	s_cbranch_execz .LBB0_358
	s_cmpk_eq_i32 s51, 0x400
	s_cselect_b64 s[6:7], -1, 0
	s_movk_i32 s18, 0x66f
	s_or_b64 s[6:7], s[6:7], vcc
	v_cmp_lt_u32_e32 vcc, s18, v136
	s_or_b64 s[6:7], s[6:7], vcc
	s_and_saveexec_b64 s[18:19], s[6:7]
	s_cbranch_execz .LBB0_357
	v_lshlrev_b32_e32 v0, 2, v94
	v_and_b32_e32 v0, 0xf0, v0
	v_lshl_or_b32 v0, v118, 8, v0
	v_mov_b32_e32 v78, v168
	v_mov_b32_e32 v79, v169
	v_mov_b32_e32 v80, v170
	v_mov_b32_e32 v81, v171
	v_pk_mul_f32 v[82:83], v[74:75], v[78:79] op_sel:[1,1] op_sel_hi:[0,1]
	v_mul_f32_e32 v0, v77, v81
	v_pk_mul_f32 v[84:85], v[74:75], v[78:79] op_sel_hi:[1,0]
	v_pk_fma_f32 v[74:75], v[74:75], v[78:79], v[82:83] op_sel_hi:[1,0,1]
	v_pk_fma_f32 v[78:79], v[76:77], v[80:81], v[0:1] op_sel_hi:[1,1,0] neg_lo:[0,0,1] neg_hi:[0,0,1]
	v_mul_f32_e32 v0, v76, v81
	v_pk_fma_f32 v[76:77], v[76:77], v[80:81], v[0:1] op_sel:[1,0,0] op_sel_hi:[0,1,0]
	v_sub_f32_e32 v74, v84, v82
	v_mov_b32_e32 v77, v76
	v_mov_b32_e32 v76, v78

.LBB0_370:
	s_and_b64 vcc, exec, s[22:23]
	s_cbranch_vccz .LBB0_372
	v_lshlrev_b32_e32 v0, 3, v137
	v_lshl_or_b32 v0, v62, 8, v0
	v_mov_b32_e32 v26, v188
	v_mov_b32_e32 v27, v189
	v_mov_b32_e32 v28, v190
	v_mov_b32_e32 v29, v191
	v_pk_mul_f32 v[30:31], v[22:23], v[26:27] op_sel:[1,1] op_sel_hi:[0,1]
	v_mul_f32_e32 v0, v25, v29
	v_pk_mul_f32 v[32:33], v[22:23], v[26:27] op_sel_hi:[1,0]
	v_pk_fma_f32 v[22:23], v[22:23], v[26:27], v[30:31] op_sel_hi:[1,0,1]
	v_pk_fma_f32 v[26:27], v[24:25], v[28:29], v[0:1] op_sel_hi:[1,1,0] neg_lo:[0,0,1] neg_hi:[0,0,1]
	v_mul_f32_e32 v0, v24, v29
	v_pk_fma_f32 v[24:25], v[24:25], v[28:29], v[0:1] op_sel:[1,0,0] op_sel_hi:[0,1,0]
	v_sub_f32_e32 v22, v32, v30
	v_mov_b32_e32 v25, v24
	v_mov_b32_e32 v24, v26

;   __device__ __forceinline__ void operator()(int m, int n, f32x4 v) const {
;     ...
;     if (n < 256) { v[0] *= 0.125f; v[1] *= 0.125f; v[2] *= 0.125f; v[3] *= 0.125f; }
;     if (m < TX && cd_rope_col(n)) v = rope4(v, rope, key, (n & 63) >> 1);
.LBB0_377:
	s_movk_i32 s0, 0x380
	v_cmp_ne_u32_e32 vcc, s0, v95
	s_and_saveexec_b64 s[0:1], vcc
	s_xor_b64 s[0:1], exec, s[0:1]
	s_cbranch_execz .LBB0_383
	s_movk_i32 s6, 0x70
	v_pk_mul_f32 v[22:23], v[20:21], s[54:55] op_sel_hi:[1,0]
	v_pk_mul_f32 v[24:25], v[18:19], s[54:55] op_sel_hi:[1,0]
	v_cmp_gt_u32_e32 vcc, s6, v136
	s_nop 1
	v_cndmask_b32_e32 v19, v19, v25, vcc
	v_cndmask_b32_e32 v18, v18, v24, vcc
	v_cndmask_b32_e32 v21, v21, v23, vcc
	v_cndmask_b32_e32 v20, v20, v22, vcc
	s_and_saveexec_b64 s[14:15], s[20:21]
	s_cbranch_execz .LBB0_382
	s_cmpk_eq_i32 s51, 0x400
	s_cselect_b64 s[6:7], -1, 0
	s_movk_i32 s20, 0x66f
	s_or_b64 s[6:7], s[6:7], vcc
	v_cmp_lt_u32_e32 vcc, s20, v136
	s_or_b64 s[6:7], s[6:7], vcc
	s_and_saveexec_b64 s[20:21], s[6:7]
	s_cbranch_execz .LBB0_381
	v_lshlrev_b32_e32 v0, 2, v94
	v_and_b32_e32 v0, 0xf0, v0
	v_lshl_or_b32 v0, v62, 8, v0
	v_mov_b32_e32 v22, v192
	v_mov_b32_e32 v23, v193
	v_mov_b32_e32 v24, v194
	v_mov_b32_e32 v25, v195
	v_pk_mul_f32 v[26:27], v[18:19], v[22:23] op_sel:[1,1] op_sel_hi:[0,1]
	v_mul_f32_e32 v0, v21, v25
	v_pk_mul_f32 v[28:29], v[18:19], v[22:23] op_sel_hi:[1,0]
	v_pk_fma_f32 v[18:19], v[18:19], v[22:23], v[26:27] op_sel_hi:[1,0,1]
	v_pk_fma_f32 v[22:23], v[20:21], v[24:25], v[0:1] op_sel_hi:[1,1,0] neg_lo:[0,0,1] neg_hi:[0,0,1]
	v_mul_f32_e32 v0, v20, v25
	v_pk_fma_f32 v[20:21], v[20:21], v[24:25], v[0:1] op_sel:[1,0,0] op_sel_hi:[0,1,0]
	v_sub_f32_e32 v18, v28, v26
	v_mov_b32_e32 v21, v20
	v_mov_b32_e32 v20, v22

.LBB0_394:
	s_and_b64 vcc, exec, s[22:23]
	s_cbranch_vccz .LBB0_396
	v_lshlrev_b32_e32 v0, 3, v137
	v_lshl_or_b32 v0, v110, 8, v0
	v_mov_b32_e32 v74, v172
	v_mov_b32_e32 v75, v173
	v_mov_b32_e32 v76, v174
	v_mov_b32_e32 v77, v175
	v_pk_mul_f32 v[78:79], v[70:71], v[74:75] op_sel:[1,1] op_sel_hi:[0,1]
	v_mul_f32_e32 v0, v73, v77
	v_pk_mul_f32 v[80:81], v[70:71], v[74:75] op_sel_hi:[1,0]
	v_pk_fma_f32 v[70:71], v[70:71], v[74:75], v[78:79] op_sel_hi:[1,0,1]
	v_pk_fma_f32 v[74:75], v[72:73], v[76:77], v[0:1] op_sel_hi:[1,1,0] neg_lo:[0,0,1] neg_hi:[0,0,1]
	v_mul_f32_e32 v0, v72, v77
	v_pk_fma_f32 v[72:73], v[72:73], v[76:77], v[0:1] op_sel:[1,0,0] op_sel_hi:[0,1,0]
	v_sub_f32_e32 v70, v80, v78
	v_mov_b32_e32 v73, v72
	v_mov_b32_e32 v72, v74

;   __device__ __forceinline__ void operator()(int m, int n, f32x4 v) const {
;     ...
;     if (n < 256) { v[0] *= 0.125f; v[1] *= 0.125f; v[2] *= 0.125f; v[3] *= 0.125f; }
;     if (m < TX && cd_rope_col(n)) v = rope4(v, rope, key, (n & 63) >> 1);
.LBB0_401:
	s_movk_i32 s0, 0x380
	v_cmp_ne_u32_e32 vcc, s0, v95
	s_and_saveexec_b64 s[0:1], vcc
	s_xor_b64 s[0:1], exec, s[0:1]
	s_cbranch_execz .LBB0_407
	s_movk_i32 s6, 0x70
	v_pk_mul_f32 v[70:71], v[68:69], s[54:55] op_sel_hi:[1,0]
	v_pk_mul_f32 v[72:73], v[66:67], s[54:55] op_sel_hi:[1,0]
	v_cmp_gt_u32_e32 vcc, s6, v136
	s_nop 1
	v_cndmask_b32_e32 v67, v67, v73, vcc
	v_cndmask_b32_e32 v66, v66, v72, vcc
	v_cndmask_b32_e32 v69, v69, v71, vcc
	v_cndmask_b32_e32 v68, v68, v70, vcc
	s_and_saveexec_b64 s[20:21], s[16:17]
	s_cbranch_execz .LBB0_406
	s_cmpk_eq_i32 s51, 0x400
	s_cselect_b64 s[6:7], -1, 0
	s_movk_i32 s16, 0x66f
	s_or_b64 s[6:7], s[6:7], vcc
	v_cmp_lt_u32_e32 vcc, s16, v136
	s_or_b64 s[6:7], s[6:7], vcc
	s_and_saveexec_b64 s[16:17], s[6:7]
	s_cbranch_execz .LBB0_405
	v_lshlrev_b32_e32 v0, 2, v94
	v_and_b32_e32 v0, 0xf0, v0
	v_lshl_or_b32 v0, v110, 8, v0
	v_mov_b32_e32 v70, v176
	v_mov_b32_e32 v71, v177
	v_mov_b32_e32 v72, v178
	v_mov_b32_e32 v73, v179
	v_pk_mul_f32 v[74:75], v[66:67], v[70:71] op_sel:[1,1] op_sel_hi:[0,1]
	v_mul_f32_e32 v0, v69, v73
	v_pk_mul_f32 v[76:77], v[66:67], v[70:71] op_sel_hi:[1,0]
	v_pk_fma_f32 v[66:67], v[66:67], v[70:71], v[74:75] op_sel_hi:[1,0,1]
	v_pk_fma_f32 v[70:71], v[68:69], v[72:73], v[0:1] op_sel_hi:[1,1,0] neg_lo:[0,0,1] neg_hi:[0,0,1]
	v_mul_f32_e32 v0, v68, v73
	v_pk_fma_f32 v[68:69], v[68:69], v[72:73], v[0:1] op_sel:[1,0,0] op_sel_hi:[0,1,0]
	v_sub_f32_e32 v66, v76, v74
	v_mov_b32_e32 v69, v68
	v_mov_b32_e32 v68, v70

.LBB0_412:
	s_and_b64 vcc, exec, s[20:21]
	s_cbranch_vccz .LBB0_414
	v_lshlrev_b32_e32 v0, 3, v137
	v_lshl_or_b32 v0, v54, 8, v0
	v_mov_b32_e32 v18, v208
	v_mov_b32_e32 v19, v209
	v_mov_b32_e32 v20, v210
	v_mov_b32_e32 v21, v211
	v_pk_mul_f32 v[22:23], v[14:15], v[18:19] op_sel:[1,1] op_sel_hi:[0,1]
	v_mul_f32_e32 v0, v17, v21
	v_pk_mul_f32 v[24:25], v[14:15], v[18:19] op_sel_hi:[1,0]
	v_pk_fma_f32 v[14:15], v[14:15], v[18:19], v[22:23] op_sel_hi:[1,0,1]
	v_pk_fma_f32 v[18:19], v[16:17], v[20:21], v[0:1] op_sel_hi:[1,1,0] neg_lo:[0,0,1] neg_hi:[0,0,1]
	v_mul_f32_e32 v0, v16, v21
	v_pk_fma_f32 v[16:17], v[16:17], v[20:21], v[0:1] op_sel:[1,0,0] op_sel_hi:[0,1,0]
	v_sub_f32_e32 v14, v24, v22
	v_mov_b32_e32 v17, v16
	v_mov_b32_e32 v16, v18

;   __device__ __forceinline__ void operator()(int m, int n, f32x4 v) const {
;     ...
;     if (n < 256) { v[0] *= 0.125f; v[1] *= 0.125f; v[2] *= 0.125f; v[3] *= 0.125f; }
;     if (m < TX && cd_rope_col(n)) v = rope4(v, rope, key, (n & 63) >> 1);
.LBB0_419:
	s_movk_i32 s0, 0x380
	v_cmp_ne_u32_e32 vcc, s0, v95
	s_and_saveexec_b64 s[0:1], vcc
	s_xor_b64 s[0:1], exec, s[0:1]
	s_cbranch_execz .LBB0_425
	s_movk_i32 s6, 0x70
	v_pk_mul_f32 v[14:15], v[12:13], s[54:55] op_sel_hi:[1,0]
	v_pk_mul_f32 v[16:17], v[10:11], s[54:55] op_sel_hi:[1,0]
	v_cmp_gt_u32_e32 vcc, s6, v136
	s_nop 1
	v_cndmask_b32_e32 v11, v11, v17, vcc
	v_cndmask_b32_e32 v10, v10, v16, vcc
	v_cndmask_b32_e32 v13, v13, v15, vcc
	v_cndmask_b32_e32 v12, v12, v14, vcc
	s_and_saveexec_b64 s[14:15], s[18:19]
	s_cbranch_execz .LBB0_424
	s_cmpk_eq_i32 s51, 0x400
	s_cselect_b64 s[6:7], -1, 0
	s_movk_i32 s18, 0x66f
	s_or_b64 s[6:7], s[6:7], vcc
	v_cmp_lt_u32_e32 vcc, s18, v136
	s_or_b64 s[6:7], s[6:7], vcc
	s_and_saveexec_b64 s[18:19], s[6:7]
	s_cbranch_execz .LBB0_423
	v_lshlrev_b32_e32 v0, 2, v94
	v_and_b32_e32 v0, 0xf0, v0
	v_lshl_or_b32 v0, v54, 8, v0
	v_mov_b32_e32 v14, v212
	v_mov_b32_e32 v15, v213
	v_mov_b32_e32 v16, v214
	v_mov_b32_e32 v17, v215
	v_pk_mul_f32 v[18:19], v[10:11], v[14:15] op_sel:[1,1] op_sel_hi:[0,1]
	v_mul_f32_e32 v0, v13, v17
	v_pk_mul_f32 v[20:21], v[10:11], v[14:15] op_sel_hi:[1,0]
	v_pk_fma_f32 v[10:11], v[10:11], v[14:15], v[18:19] op_sel_hi:[1,0,1]
	v_pk_fma_f32 v[14:15], v[12:13], v[16:17], v[0:1] op_sel_hi:[1,1,0] neg_lo:[0,0,1] neg_hi:[0,0,1]
	v_mul_f32_e32 v0, v12, v17
	v_pk_fma_f32 v[12:13], v[12:13], v[16:17], v[0:1] op_sel:[1,0,0] op_sel_hi:[0,1,0]
	v_sub_f32_e32 v10, v20, v18
	v_mov_b32_e32 v13, v12
	v_mov_b32_e32 v12, v14

.LBB0_436:
	s_and_b64 vcc, exec, s[14:15]
	s_cbranch_vccz .LBB0_438
	v_lshlrev_b32_e32 v0, 3, v137
	v_lshl_or_b32 v0, v46, 8, v0
	v_mov_b32_e32 v10, v216
	v_mov_b32_e32 v11, v217
	v_mov_b32_e32 v12, v218
	v_mov_b32_e32 v13, v219
	v_pk_mul_f32 v[14:15], v[6:7], v[10:11] op_sel:[1,1] op_sel_hi:[0,1]
	v_mul_f32_e32 v0, v9, v13
	v_pk_mul_f32 v[16:17], v[6:7], v[10:11] op_sel_hi:[1,0]
	v_pk_fma_f32 v[6:7], v[6:7], v[10:11], v[14:15] op_sel_hi:[1,0,1]
	v_pk_fma_f32 v[10:11], v[8:9], v[12:13], v[0:1] op_sel_hi:[1,1,0] neg_lo:[0,0,1] neg_hi:[0,0,1]
	v_mul_f32_e32 v0, v8, v13
	v_pk_fma_f32 v[8:9], v[8:9], v[12:13], v[0:1] op_sel:[1,0,0] op_sel_hi:[0,1,0]
	v_sub_f32_e32 v6, v16, v14
	v_mov_b32_e32 v9, v8
	v_mov_b32_e32 v8, v10

;   __device__ __forceinline__ void operator()(int m, int n, f32x4 v) const {
;     ...
;     if (n < 256) { v[0] *= 0.125f; v[1] *= 0.125f; v[2] *= 0.125f; v[3] *= 0.125f; }
;     if (m < TX && cd_rope_col(n)) v = rope4(v, rope, key, (n & 63) >> 1);
.LBB0_443:
	s_movk_i32 s0, 0x380
	v_cmp_ne_u32_e32 vcc, s0, v95
	s_and_saveexec_b64 s[0:1], vcc
	s_xor_b64 s[0:1], exec, s[0:1]
	s_cbranch_execz .LBB0_449
	s_movk_i32 s6, 0x70
	v_pk_mul_f32 v[6:7], v[4:5], s[54:55] op_sel_hi:[1,0]
	v_pk_mul_f32 v[8:9], v[2:3], s[54:55] op_sel_hi:[1,0]
	v_cmp_gt_u32_e32 vcc, s6, v136
	s_nop 1
	v_cndmask_b32_e32 v3, v3, v9, vcc
	v_cndmask_b32_e32 v2, v2, v8, vcc
	v_cndmask_b32_e32 v5, v5, v7, vcc
	v_cndmask_b32_e32 v4, v4, v6, vcc
	s_and_saveexec_b64 s[10:11], s[16:17]
	s_cbranch_execz .LBB0_448
	s_cmpk_eq_i32 s51, 0x400
	s_cselect_b64 s[6:7], -1, 0
	s_movk_i32 s12, 0x66f
	s_or_b64 s[6:7], s[6:7], vcc
	v_cmp_lt_u32_e32 vcc, s12, v136
	s_or_b64 s[6:7], s[6:7], vcc
	s_and_saveexec_b64 s[12:13], s[6:7]
	s_cbranch_execz .LBB0_447
	v_lshlrev_b32_e32 v0, 2, v94
	v_and_b32_e32 v0, 0xf0, v0
	v_lshl_or_b32 v0, v46, 8, v0
	v_mov_b32_e32 v6, v220
	v_mov_b32_e32 v7, v221
	v_mov_b32_e32 v8, v222
	v_mov_b32_e32 v9, v223
	v_pk_mul_f32 v[10:11], v[2:3], v[6:7] op_sel:[1,1] op_sel_hi:[0,1]
	v_mul_f32_e32 v0, v5, v9
	v_pk_mul_f32 v[12:13], v[2:3], v[6:7] op_sel_hi:[1,0]
	v_pk_fma_f32 v[2:3], v[2:3], v[6:7], v[10:11] op_sel_hi:[1,0,1]
	v_pk_fma_f32 v[6:7], v[4:5], v[8:9], v[0:1] op_sel_hi:[1,1,0] neg_lo:[0,0,1] neg_hi:[0,0,1]
	v_mul_f32_e32 v0, v4, v9
	v_pk_fma_f32 v[4:5], v[4:5], v[8:9], v[0:1] op_sel:[1,0,0] op_sel_hi:[0,1,0]
	v_sub_f32_e32 v2, v12, v10
	v_mov_b32_e32 v5, v4
	v_mov_b32_e32 v4, v6

; __device__ __forceinline__ float lo_bf(unsigned u) { return __uint_as_float(u << 16); }
; __device__ __forceinline__ float hi_bf(unsigned u) { return __uint_as_float(u & 0xffff0000u); }
; template <class Epi>
; __device__ __forceinline__ void gemm_tile(const u16* __restrict__ A, int lda, const u16* __restrict__ Wt, int K,
;                                           int m0, int n0, char* sbase, const Epi& epi) {
;     ...
;       for (int ai = 0; ai < 2; ++ai) {
;         float4 gg[2][2];
;         uint2 rr[2][4][2];
; #pragma unroll
;         for (int bj = 0; bj < 2; ++bj)
; #pragma unroll
;           for (int n = 0; n < 2; ++n) gg[bj][n] = epi.loadG(m0, n0 + bj * 128 + wc * 32 + n * 16 + fq * 4);
; #pragma unroll
;         for (int bj = 0; bj < 2; ++bj)
; #pragma unroll
;           for (int m = 0; m < 4; ++m)
; #pragma unroll
;             for (int n = 0; n < 2; ++n)
;               rr[bj][m][n] = epi.loadR(m0 + ai * 128 + wr * 64 + m * 16 + fr, n0 + bj * 128 + wc * 32 + n * 16 + fq * 4);
; #pragma unroll
;         for (int bj = 0; bj < 2; ++bj)
; #pragma unroll
;           for (int m = 0; m < 4; ++m)
; #pragma unroll
;             for (int n = 0; n < 2; ++n)
;               epi.apply(m0 + ai * 128 + wr * 64 + m * 16 + fr, n0 + bj * 128 + wc * 32 + n * 16 + fq * 4, acc[ai][bj][m][n],
;                         rr[bj][m][n], gg[bj][n]);
;   __device__ __forceinline__ float4 loadG(int m, int n) const { return *(const float4*)(gate + (size_t)modrow(m) * 6144 + n); }
;   __device__ __forceinline__ void apply(int m, int n, f32x4 v, uint2 a, float4 g) const {
;     f32x4 o;
;     o[0] = lo_bf(a.x) + mul * g.x * v[0]; o[1] = hi_bf(a.x) + mul * g.y * v[1];
;     o[2] = lo_bf(a.y) + mul * g.z * v[2]; o[3] = hi_bf(a.y) + mul * g.w * v[3];
;     store4bf(p->Rb + (size_t)m * 1024 + n, o);
.LBB0_776:
	s_or_b64 exec, exec, s[0:1]
	v_lshlrev_b32_e32 v0, 5, v146
	v_lshlrev_b32_e32 v130, 2, v147
	v_or_b32_e32 v131, s34, v145
	s_and_b64 vcc, exec, s[8:9]
	v_or3_b32 v210, v0, v130, s46
	v_add_u32_e32 v138, v131, v148
	s_cbranch_vccz .LBB0_778
	v_or_b32_e32 v142, 16, v138
	v_ashrrev_i32_e32 v143, 31, v142
	v_lshlrev_b64 v[142:143], 11, v[142:143]
	v_lshlrev_b32_e32 v0, 1, v210
	v_lshl_add_u64 v[142:143], s[38:39], 0, v[142:143]
	s_min_i32 s0, s34, 0x10000
	v_or_b32_e32 v130, 48, v138
	v_lshl_add_u64 v[152:153], v[142:143], 0, v[0:1]
	v_or_b32_e32 v142, 32, v138
	s_lshr_b32 s0, s0, 11
	v_ashrrev_i32_e32 v131, 31, v130
	v_ashrrev_i32_e32 v139, 31, v138
	v_ashrrev_i32_e32 v143, 31, v142
	s_mulk_i32 s0, 0x6000
	v_lshlrev_b64 v[130:131], 11, v[130:131]
	v_lshlrev_b64 v[132:133], 11, v[138:139]
	v_lshlrev_b64 v[142:143], 11, v[142:143]
	s_add_u32 s16, s6, s0
	v_lshl_add_u64 v[130:131], s[38:39], 0, v[130:131]
	v_lshl_add_u64 v[132:133], s[38:39], 0, v[132:133]
	v_lshl_add_u64 v[142:143], s[38:39], 0, v[142:143]
	s_addc_u32 s17, s7, 0
	v_lshlrev_b32_e32 v211, 2, v210
	v_lshl_add_u64 v[140:141], v[132:133], 0, v[0:1]
	v_lshl_add_u64 v[146:147], v[142:143], 0, v[0:1]
	v_lshl_add_u64 v[142:143], v[130:131], 0, v[0:1]
	global_load_dwordx2 v[132:133], v[140:141], off
	global_load_dwordx2 v[134:135], v[140:141], off offset:32
	global_load_dwordx2 v[168:169], v[152:153], off
	global_load_dwordx2 v[170:171], v[152:153], off offset:32
	global_load_dwordx2 v[172:173], v[146:147], off
	global_load_dwordx2 v[174:175], v[146:147], off offset:32
	global_load_dwordx2 v[176:177], v[142:143], off
	global_load_dwordx2 v[178:179], v[142:143], off offset:32
	global_load_dwordx2 v[130:131], v[140:141], off offset:256
	global_load_dwordx2 v[160:161], v[140:141], off offset:288
	global_load_dwordx2 v[158:159], v[152:153], off offset:256
	global_load_dwordx2 v[156:157], v[152:153], off offset:288
	global_load_dwordx2 v[154:155], v[146:147], off offset:256
	global_load_dwordx2 v[150:151], v[146:147], off offset:288
	global_load_dwordx2 v[148:149], v[142:143], off offset:256
	global_load_dwordx2 v[144:145], v[142:143], off offset:288
	global_load_dwordx4 v[162:165], v211, s[16:17]
	global_load_dwordx4 v[236:239], v211, s[16:17]
	global_load_dwordx4 v[240:243], v211, s[16:17] offset:64
	global_load_dwordx4 v[244:247], v211, s[16:17] offset:512
	global_load_dwordx4 v[248:251], v211, s[16:17] offset:576
	s_mov_b64 s[0:1], 0x40000
	s_waitcnt vmcnt(0)
	v_lshlrev_b32_e32 v166, 16, v132
	v_and_b32_e32 v167, 0xffff0000, v132
	v_lshlrev_b32_e32 v132, 16, v133
	v_and_b32_e32 v133, 0xffff0000, v133
	v_pk_mul_f32 v[180:181], v[136:137], v[162:163]
	s_nop 0
	v_pk_fma_f32 v[162:163], v[126:127], v[180:181], v[166:167]
	v_pk_mul_f32 v[182:183], v[136:137], v[164:165]
	v_mov_b32_e32 v164, v240
	v_mov_b32_e32 v165, v241
	v_mov_b32_e32 v166, v242
	v_mov_b32_e32 v167, v243
	v_pk_fma_f32 v[132:133], v[128:129], v[182:183], v[132:133]
	v_cvt_pk_bf16_f32 v162, v162, v163
	v_cvt_pk_bf16_f32 v163, v132, v133
	v_lshlrev_b32_e32 v132, 16, v134
	v_and_b32_e32 v133, 0xffff0000, v134
	v_lshlrev_b32_e32 v134, 16, v135
	v_and_b32_e32 v135, 0xffff0000, v135
	v_pk_mul_f32 v[184:185], v[136:137], v[164:165]
	v_pk_mul_f32 v[186:187], v[136:137], v[166:167]
	v_pk_fma_f32 v[132:133], v[122:123], v[184:185], v[132:133]
	v_pk_fma_f32 v[134:135], v[124:125], v[186:187], v[134:135]
	v_cvt_pk_bf16_f32 v164, v132, v133
	v_cvt_pk_bf16_f32 v165, v134, v135
	v_lshlrev_b32_e32 v132, 16, v168
	v_and_b32_e32 v133, 0xffff0000, v168
	v_lshlrev_b32_e32 v134, 16, v169
	v_and_b32_e32 v135, 0xffff0000, v169
	v_pk_fma_f32 v[132:133], v[118:119], v[180:181], v[132:133]
	v_pk_fma_f32 v[134:135], v[120:121], v[182:183], v[134:135]
	v_cvt_pk_bf16_f32 v166, v132, v133
	v_cvt_pk_bf16_f32 v167, v134, v135
	v_lshlrev_b32_e32 v132, 16, v170
	v_and_b32_e32 v133, 0xffff0000, v170
	v_lshlrev_b32_e32 v134, 16, v171
	v_and_b32_e32 v135, 0xffff0000, v171
	v_pk_fma_f32 v[132:133], v[114:115], v[184:185], v[132:133]
	v_pk_fma_f32 v[134:135], v[116:117], v[186:187], v[134:135]
	v_cvt_pk_bf16_f32 v168, v132, v133
	v_cvt_pk_bf16_f32 v169, v134, v135
	v_lshlrev_b32_e32 v132, 16, v172
	v_and_b32_e32 v133, 0xffff0000, v172
	v_lshlrev_b32_e32 v134, 16, v173
	v_and_b32_e32 v135, 0xffff0000, v173
	v_pk_fma_f32 v[132:133], v[110:111], v[180:181], v[132:133]
	v_pk_fma_f32 v[134:135], v[112:113], v[182:183], v[134:135]
	v_cvt_pk_bf16_f32 v170, v132, v133
	v_cvt_pk_bf16_f32 v171, v134, v135
	v_lshlrev_b32_e32 v132, 16, v174
	v_and_b32_e32 v133, 0xffff0000, v174
	v_lshlrev_b32_e32 v134, 16, v175
	v_and_b32_e32 v135, 0xffff0000, v175
	v_pk_fma_f32 v[132:133], v[106:107], v[184:185], v[132:133]
	v_pk_fma_f32 v[134:135], v[108:109], v[186:187], v[134:135]
	v_cvt_pk_bf16_f32 v172, v132, v133
	v_cvt_pk_bf16_f32 v173, v134, v135
	v_lshlrev_b32_e32 v132, 16, v176
	v_and_b32_e32 v133, 0xffff0000, v176
	v_lshlrev_b32_e32 v134, 16, v177
	v_and_b32_e32 v135, 0xffff0000, v177
	v_pk_fma_f32 v[132:133], v[102:103], v[180:181], v[132:133]
	v_pk_fma_f32 v[134:135], v[104:105], v[182:183], v[134:135]
	v_mov_b32_e32 v180, v244
	v_mov_b32_e32 v181, v245
	v_mov_b32_e32 v182, v246
	v_mov_b32_e32 v183, v247
	v_cvt_pk_bf16_f32 v174, v132, v133
	v_lshlrev_b32_e32 v132, 16, v178
	v_and_b32_e32 v133, 0xffff0000, v178
	v_pk_fma_f32 v[132:133], v[98:99], v[184:185], v[132:133]
	v_cvt_pk_bf16_f32 v175, v134, v135
	v_lshlrev_b32_e32 v134, 16, v179
	v_and_b32_e32 v135, 0xffff0000, v179
	v_cvt_pk_bf16_f32 v176, v132, v133
	v_lshlrev_b32_e32 v132, 16, v130
	v_and_b32_e32 v133, 0xffff0000, v130
	v_lshlrev_b32_e32 v130, 16, v131
	v_and_b32_e32 v131, 0xffff0000, v131
; __device__ __forceinline__ float lo_bf(unsigned u) { return __uint_as_float(u << 16); }
; __device__ __forceinline__ float hi_bf(unsigned u) { return __uint_as_float(u & 0xffff0000u); }
; template <class Epi>
; __device__ __forceinline__ void gemm_tile(const u16* __restrict__ A, int lda, const u16* __restrict__ Wt, int K,
;                                           int m0, int n0, char* sbase, const Epi& epi) {
;     ...
;       for (int ai = 0; ai < 2; ++ai) {
;         float4 gg[2][2];
;         uint2 rr[2][4][2];
; #pragma unroll
;         for (int bj = 0; bj < 2; ++bj)
; #pragma unroll
;           for (int n = 0; n < 2; ++n) gg[bj][n] = epi.loadG(m0, n0 + bj * 128 + wc * 32 + n * 16 + fq * 4);
; #pragma unroll
;         for (int bj = 0; bj < 2; ++bj)
; #pragma unroll
;           for (int m = 0; m < 4; ++m)
; #pragma unroll
;             for (int n = 0; n < 2; ++n)
;               rr[bj][m][n] = epi.loadR(m0 + ai * 128 + wr * 64 + m * 16 + fr, n0 + bj * 128 + wc * 32 + n * 16 + fq * 4);
; #pragma unroll
;         for (int bj = 0; bj < 2; ++bj)
; #pragma unroll
;           for (int m = 0; m < 4; ++m)
; #pragma unroll
;             for (int n = 0; n < 2; ++n)
;               epi.apply(m0 + ai * 128 + wr * 64 + m * 16 + fr, n0 + bj * 128 + wc * 32 + n * 16 + fq * 4, acc[ai][bj][m][n],
;                         rr[bj][m][n], gg[bj][n]);
;   __device__ __forceinline__ float4 loadG(int m, int n) const { return *(const float4*)(gate + (size_t)modrow(m) * 6144 + n); }
;   __device__ __forceinline__ void apply(int m, int n, f32x4 v, uint2 a, float4 g) const {
;     f32x4 o;
;     o[0] = lo_bf(a.x) + mul * g.x * v[0]; o[1] = hi_bf(a.x) + mul * g.y * v[1];
;     o[2] = lo_bf(a.y) + mul * g.z * v[2]; o[3] = hi_bf(a.y) + mul * g.w * v[3];
;     store4bf(p->Rb + (size_t)m * 1024 + n, o);
	v_pk_fma_f32 v[134:135], v[100:101], v[186:187], v[134:135]
	v_lshlrev_b32_e32 v184, 16, v160
	v_and_b32_e32 v185, 0xffff0000, v160
	v_lshlrev_b32_e32 v160, 16, v161
	v_and_b32_e32 v161, 0xffff0000, v161
	v_cvt_pk_bf16_f32 v177, v134, v135
	v_pk_mul_f32 v[180:181], v[136:137], v[180:181]
	v_pk_mul_f32 v[178:179], v[136:137], v[182:183]
	v_pk_fma_f32 v[132:133], v[94:95], v[180:181], v[132:133]
	v_pk_fma_f32 v[130:131], v[96:97], v[178:179], v[130:131]
	v_cvt_pk_bf16_f32 v182, v132, v133
	v_cvt_pk_bf16_f32 v183, v130, v131
	v_mov_b32_e32 v130, v248
	v_mov_b32_e32 v131, v249
	v_mov_b32_e32 v132, v250
	v_mov_b32_e32 v133, v251
	s_nop 0
	global_store_dwordx2 v[140:141], v[162:163], off
	global_store_dwordx2 v[140:141], v[164:165], off offset:32
	global_store_dwordx2 v[152:153], v[166:167], off
	global_store_dwordx2 v[152:153], v[168:169], off offset:32
	global_store_dwordx2 v[146:147], v[170:171], off
	global_store_dwordx2 v[146:147], v[172:173], off offset:32
	global_store_dwordx2 v[142:143], v[174:175], off
	global_store_dwordx2 v[142:143], v[176:177], off offset:32
	global_store_dwordx2 v[140:141], v[182:183], off offset:256
	v_pk_mul_f32 v[130:131], v[136:137], v[130:131]
	v_pk_mul_f32 v[132:133], v[136:137], v[132:133]
	v_pk_fma_f32 v[134:135], v[90:91], v[130:131], v[184:185]
	v_pk_fma_f32 v[160:161], v[92:93], v[132:133], v[160:161]
	v_cvt_pk_bf16_f32 v134, v134, v135
	v_cvt_pk_bf16_f32 v135, v160, v161
	global_store_dwordx2 v[140:141], v[134:135], off offset:288
	v_lshlrev_b32_e32 v134, 16, v158
	v_and_b32_e32 v135, 0xffff0000, v158
	v_lshlrev_b32_e32 v158, 16, v159
	v_and_b32_e32 v159, 0xffff0000, v159
	v_pk_fma_f32 v[134:135], v[86:87], v[180:181], v[134:135]
	v_pk_fma_f32 v[158:159], v[88:89], v[178:179], v[158:159]
	v_cvt_pk_bf16_f32 v134, v134, v135
	v_cvt_pk_bf16_f32 v135, v158, v159
	global_store_dwordx2 v[152:153], v[134:135], off offset:256
	v_lshlrev_b32_e32 v134, 16, v156
	v_and_b32_e32 v135, 0xffff0000, v156
	v_lshlrev_b32_e32 v156, 16, v157
	v_and_b32_e32 v157, 0xffff0000, v157
	v_pk_fma_f32 v[134:135], v[82:83], v[130:131], v[134:135]
	v_pk_fma_f32 v[156:157], v[84:85], v[132:133], v[156:157]
	v_cvt_pk_bf16_f32 v134, v134, v135
	v_cvt_pk_bf16_f32 v135, v156, v157
	global_store_dwordx2 v[152:153], v[134:135], off offset:288
	v_lshlrev_b32_e32 v134, 16, v154
	v_and_b32_e32 v135, 0xffff0000, v154
	v_lshlrev_b32_e32 v152, 16, v155
	v_and_b32_e32 v153, 0xffff0000, v155
	v_pk_fma_f32 v[134:135], v[78:79], v[180:181], v[134:135]
	v_pk_fma_f32 v[152:153], v[80:81], v[178:179], v[152:153]
	v_cvt_pk_bf16_f32 v134, v134, v135
	v_cvt_pk_bf16_f32 v135, v152, v153
	global_store_dwordx2 v[146:147], v[134:135], off offset:256
	v_lshlrev_b32_e32 v134, 16, v150
	v_and_b32_e32 v135, 0xffff0000, v150
	v_lshlrev_b32_e32 v150, 16, v151
	v_and_b32_e32 v151, 0xffff0000, v151
	v_pk_fma_f32 v[134:135], v[74:75], v[130:131], v[134:135]
	v_pk_fma_f32 v[150:151], v[76:77], v[132:133], v[150:151]
	v_cvt_pk_bf16_f32 v134, v134, v135
	v_cvt_pk_bf16_f32 v135, v150, v151
	global_store_dwordx2 v[146:147], v[134:135], off offset:288
	v_lshlrev_b32_e32 v134, 16, v148
	v_and_b32_e32 v135, 0xffff0000, v148
	v_lshlrev_b32_e32 v146, 16, v149
	v_and_b32_e32 v147, 0xffff0000, v149
	v_pk_fma_f32 v[134:135], v[70:71], v[180:181], v[134:135]
	v_pk_fma_f32 v[146:147], v[72:73], v[178:179], v[146:147]
	v_lshl_add_u64 v[154:155], v[140:141], 0, s[0:1]
	s_mov_b32 s0, 0x40000
	v_cvt_pk_bf16_f32 v134, v134, v135
	v_cvt_pk_bf16_f32 v135, v146, v147
	v_add_co_u32_e32 v162, vcc, s0, v140
	global_store_dwordx2 v[142:143], v[134:135], off offset:256
	v_lshlrev_b32_e32 v134, 16, v144
	v_and_b32_e32 v135, 0xffff0000, v144
	v_addc_co_u32_e32 v163, vcc, 0, v141, vcc
	s_mov_b32 s0, 0x48000
	v_pk_fma_f32 v[130:131], v[66:67], v[130:131], v[134:135]
	v_lshlrev_b32_e32 v134, 16, v145
	v_and_b32_e32 v135, 0xffff0000, v145
	v_add_co_u32_e32 v164, vcc, s0, v140
	s_mov_b64 s[0:1], 0x50000
	v_pk_fma_f32 v[132:133], v[68:69], v[132:133], v[134:135]
	v_addc_co_u32_e32 v165, vcc, 0, v141, vcc
	v_lshl_add_u64 v[146:147], v[140:141], 0, s[0:1]
	s_mov_b32 s0, 0x50000
	v_cvt_pk_bf16_f32 v130, v130, v131
	v_cvt_pk_bf16_f32 v131, v132, v133
	v_add_co_u32_e32 v166, vcc, s0, v140
	s_mov_b64 s[0:1], 0x58000
	global_store_dwordx2 v[142:143], v[130:131], off offset:288
	v_addc_co_u32_e32 v167, vcc, 0, v141, vcc
	v_lshl_add_u64 v[142:143], v[140:141], 0, s[0:1]
	s_mov_b32 s0, 0x58000
	v_add_co_u32_e32 v168, vcc, s0, v140
	global_load_dwordx2 v[134:135], v[162:163], off
	global_load_dwordx2 v[178:179], v[154:155], off offset:32
	v_addc_co_u32_e32 v169, vcc, 0, v141, vcc
	v_lshl_add_u64 v[150:151], v[140:141], 0, s[28:29]
	global_load_dwordx2 v[180:181], v[164:165], off
	global_load_dwordx2 v[182:183], v[150:151], off offset:32
	global_load_dwordx2 v[184:185], v[166:167], off
	global_load_dwordx2 v[186:187], v[146:147], off offset:32
	global_load_dwordx2 v[188:189], v[168:169], off
	global_load_dwordx2 v[132:133], v[142:143], off offset:32
	global_load_dwordx2 v[130:131], v[154:155], off offset:256
	global_load_dwordx2 v[170:171], v[154:155], off offset:288
	global_load_dwordx2 v[160:161], v[150:151], off offset:256
	global_load_dwordx2 v[158:159], v[150:151], off offset:288
	global_load_dwordx2 v[156:157], v[146:147], off offset:256
	global_load_dwordx2 v[152:153], v[146:147], off offset:288
	global_load_dwordx2 v[148:149], v[142:143], off offset:256
	v_mov_b32_e32 v172, v236
	v_mov_b32_e32 v173, v237
	v_mov_b32_e32 v174, v238
	v_mov_b32_e32 v175, v239
	global_load_dwordx2 v[144:145], v[142:143], off offset:288
	s_mov_b64 s[0:1], 0x120
	v_lshl_add_u64 v[140:141], v[142:143], 0, s[0:1]
	s_waitcnt vmcnt(0)
; __device__ __forceinline__ float lo_bf(unsigned u) { return __uint_as_float(u << 16); }
; __device__ __forceinline__ float hi_bf(unsigned u) { return __uint_as_float(u & 0xffff0000u); }
; template <class Epi>
; __device__ __forceinline__ void gemm_tile(const u16* __restrict__ A, int lda, const u16* __restrict__ Wt, int K,
;                                           int m0, int n0, char* sbase, const Epi& epi) {
;     ...
;       for (int ai = 0; ai < 2; ++ai) {
;         float4 gg[2][2];
;         uint2 rr[2][4][2];
; #pragma unroll
;         for (int bj = 0; bj < 2; ++bj)
; #pragma unroll
;           for (int n = 0; n < 2; ++n) gg[bj][n] = epi.loadG(m0, n0 + bj * 128 + wc * 32 + n * 16 + fq * 4);
; #pragma unroll
;         for (int bj = 0; bj < 2; ++bj)
; #pragma unroll
;           for (int m = 0; m < 4; ++m)
; #pragma unroll
;             for (int n = 0; n < 2; ++n)
;               rr[bj][m][n] = epi.loadR(m0 + ai * 128 + wr * 64 + m * 16 + fr, n0 + bj * 128 + wc * 32 + n * 16 + fq * 4);
; #pragma unroll
;         for (int bj = 0; bj < 2; ++bj)
; #pragma unroll
;           for (int m = 0; m < 4; ++m)
; #pragma unroll
;             for (int n = 0; n < 2; ++n)
;               epi.apply(m0 + ai * 128 + wr * 64 + m * 16 + fr, n0 + bj * 128 + wc * 32 + n * 16 + fq * 4, acc[ai][bj][m][n],
;                         rr[bj][m][n], gg[bj][n]);
;   __device__ __forceinline__ float4 loadG(int m, int n) const { return *(const float4*)(gate + (size_t)modrow(m) * 6144 + n); }
;   __device__ __forceinline__ void apply(int m, int n, f32x4 v, uint2 a, float4 g) const {
;     f32x4 o;
;     o[0] = lo_bf(a.x) + mul * g.x * v[0]; o[1] = hi_bf(a.x) + mul * g.y * v[1];
;     o[2] = lo_bf(a.y) + mul * g.z * v[2]; o[3] = hi_bf(a.y) + mul * g.w * v[3];
;     store4bf(p->Rb + (size_t)m * 1024 + n, o);
	v_lshlrev_b32_e32 v176, 16, v134
	v_and_b32_e32 v177, 0xffff0000, v134
	v_lshlrev_b32_e32 v134, 16, v135
	v_and_b32_e32 v135, 0xffff0000, v135
	v_pk_mul_f32 v[190:191], v[136:137], v[172:173]
	s_nop 0
	v_pk_fma_f32 v[172:173], v[62:63], v[190:191], v[176:177]
	v_pk_mul_f32 v[192:193], v[136:137], v[174:175]
	v_mov_b32_e32 v174, v240
	v_mov_b32_e32 v175, v241
	v_mov_b32_e32 v176, v242
	v_mov_b32_e32 v177, v243
	v_pk_fma_f32 v[134:135], v[64:65], v[192:193], v[134:135]
	v_cvt_pk_bf16_f32 v172, v172, v173
	v_cvt_pk_bf16_f32 v173, v134, v135
	v_lshlrev_b32_e32 v134, 16, v178
	v_and_b32_e32 v135, 0xffff0000, v178
	v_pk_mul_f32 v[194:195], v[136:137], v[174:175]
	v_lshlrev_b32_e32 v174, 16, v179
	v_and_b32_e32 v175, 0xffff0000, v179
	v_pk_mul_f32 v[202:203], v[136:137], v[176:177]
	v_pk_fma_f32 v[134:135], v[58:59], v[194:195], v[134:135]
	v_pk_fma_f32 v[176:177], v[60:61], v[202:203], v[174:175]
	v_cvt_pk_bf16_f32 v174, v134, v135
	v_cvt_pk_bf16_f32 v175, v176, v177
	v_lshlrev_b32_e32 v134, 16, v180
	v_and_b32_e32 v135, 0xffff0000, v180
	v_lshlrev_b32_e32 v176, 16, v181
	v_and_b32_e32 v177, 0xffff0000, v181
	v_pk_fma_f32 v[134:135], v[54:55], v[190:191], v[134:135]
	v_pk_fma_f32 v[178:179], v[56:57], v[192:193], v[176:177]
	v_cvt_pk_bf16_f32 v176, v134, v135
	v_cvt_pk_bf16_f32 v177, v178, v179
	v_lshlrev_b32_e32 v134, 16, v182
	v_and_b32_e32 v135, 0xffff0000, v182
	v_lshlrev_b32_e32 v178, 16, v183
	v_and_b32_e32 v179, 0xffff0000, v183
	v_pk_fma_f32 v[134:135], v[50:51], v[194:195], v[134:135]
	v_pk_fma_f32 v[180:181], v[52:53], v[202:203], v[178:179]
	v_cvt_pk_bf16_f32 v178, v134, v135
	v_cvt_pk_bf16_f32 v179, v180, v181
	v_lshlrev_b32_e32 v134, 16, v184
	v_and_b32_e32 v135, 0xffff0000, v184
	v_lshlrev_b32_e32 v180, 16, v185
	v_and_b32_e32 v181, 0xffff0000, v185
	v_pk_fma_f32 v[134:135], v[46:47], v[190:191], v[134:135]
	v_pk_fma_f32 v[182:183], v[48:49], v[192:193], v[180:181]
	v_cvt_pk_bf16_f32 v180, v134, v135
	v_cvt_pk_bf16_f32 v181, v182, v183
	v_lshlrev_b32_e32 v134, 16, v186
	v_and_b32_e32 v135, 0xffff0000, v186
	v_lshlrev_b32_e32 v182, 16, v187
	v_and_b32_e32 v183, 0xffff0000, v187
	v_pk_fma_f32 v[134:135], v[42:43], v[194:195], v[134:135]
	v_pk_fma_f32 v[184:185], v[44:45], v[202:203], v[182:183]
	v_cvt_pk_bf16_f32 v182, v134, v135
	v_cvt_pk_bf16_f32 v183, v184, v185
	v_lshlrev_b32_e32 v134, 16, v188
	v_and_b32_e32 v135, 0xffff0000, v188
	v_lshlrev_b32_e32 v184, 16, v189
	v_and_b32_e32 v185, 0xffff0000, v189
	v_pk_fma_f32 v[134:135], v[38:39], v[190:191], v[134:135]
	v_pk_fma_f32 v[186:187], v[40:41], v[192:193], v[184:185]
	v_mov_b32_e32 v190, v244
	v_mov_b32_e32 v191, v245
	v_mov_b32_e32 v192, v246
	v_mov_b32_e32 v193, v247
	v_cvt_pk_bf16_f32 v184, v134, v135
	v_lshlrev_b32_e32 v134, 16, v132
	v_and_b32_e32 v135, 0xffff0000, v132
	v_lshlrev_b32_e32 v132, 16, v133
	v_and_b32_e32 v133, 0xffff0000, v133
	v_pk_fma_f32 v[132:133], v[36:37], v[202:203], v[132:133]
	v_cvt_pk_bf16_f32 v185, v186, v187
	v_cvt_pk_bf16_f32 v187, v132, v133
	v_lshlrev_b32_e32 v132, 16, v130
	v_and_b32_e32 v133, 0xffff0000, v130
	v_lshlrev_b32_e32 v130, 16, v131
	v_and_b32_e32 v131, 0xffff0000, v131
	v_pk_fma_f32 v[134:135], v[34:35], v[194:195], v[134:135]
	v_lshlrev_b32_e32 v194, 16, v170
	v_and_b32_e32 v195, 0xffff0000, v170
	v_lshlrev_b32_e32 v170, 16, v171
	v_and_b32_e32 v171, 0xffff0000, v171
	v_cvt_pk_bf16_f32 v186, v134, v135
	v_pk_mul_f32 v[190:191], v[136:137], v[190:191]
	v_pk_mul_f32 v[188:189], v[136:137], v[192:193]
	v_pk_fma_f32 v[132:133], v[30:31], v[190:191], v[132:133]
	v_pk_fma_f32 v[130:131], v[32:33], v[188:189], v[130:131]
	v_cvt_pk_bf16_f32 v192, v132, v133
	v_cvt_pk_bf16_f32 v193, v130, v131
	v_mov_b32_e32 v130, v248
	v_mov_b32_e32 v131, v249
	v_mov_b32_e32 v132, v250
	v_mov_b32_e32 v133, v251
	s_nop 0
	global_store_dwordx2 v[162:163], v[172:173], off
	global_store_dwordx2 v[154:155], v[174:175], off offset:32
	global_store_dwordx2 v[164:165], v[176:177], off
	global_store_dwordx2 v[150:151], v[178:179], off offset:32
	global_store_dwordx2 v[166:167], v[180:181], off
	global_store_dwordx2 v[146:147], v[182:183], off offset:32
	global_store_dwordx2 v[168:169], v[184:185], off
	global_store_dwordx2 v[142:143], v[186:187], off offset:32
	global_store_dwordx2 v[154:155], v[192:193], off offset:256
	v_pk_mul_f32 v[130:131], v[136:137], v[130:131]
	v_pk_mul_f32 v[132:133], v[136:137], v[132:133]
	v_pk_fma_f32 v[134:135], v[26:27], v[130:131], v[194:195]
	v_pk_fma_f32 v[162:163], v[28:29], v[132:133], v[170:171]
	v_cvt_pk_bf16_f32 v134, v134, v135
	v_cvt_pk_bf16_f32 v135, v162, v163
	global_store_dwordx2 v[154:155], v[134:135], off offset:288
	v_lshlrev_b32_e32 v134, 16, v160
	v_and_b32_e32 v135, 0xffff0000, v160
	v_lshlrev_b32_e32 v154, 16, v161
	v_and_b32_e32 v155, 0xffff0000, v161
	v_pk_fma_f32 v[134:135], v[22:23], v[190:191], v[134:135]
	v_pk_fma_f32 v[154:155], v[24:25], v[188:189], v[154:155]
	v_cvt_pk_bf16_f32 v134, v134, v135
	v_cvt_pk_bf16_f32 v135, v154, v155
	global_store_dwordx2 v[150:151], v[134:135], off offset:256
	v_lshlrev_b32_e32 v134, 16, v158
	v_and_b32_e32 v135, 0xffff0000, v158
	v_lshlrev_b32_e32 v154, 16, v159
	v_and_b32_e32 v155, 0xffff0000, v159
	v_pk_fma_f32 v[134:135], v[18:19], v[130:131], v[134:135]
	v_pk_fma_f32 v[154:155], v[20:21], v[132:133], v[154:155]
	v_cvt_pk_bf16_f32 v134, v134, v135
	v_cvt_pk_bf16_f32 v135, v154, v155
	global_store_dwordx2 v[150:151], v[134:135], off offset:288
	v_lshlrev_b32_e32 v134, 16, v156
	v_and_b32_e32 v135, 0xffff0000, v156
	v_lshlrev_b32_e32 v150, 16, v157
	v_and_b32_e32 v151, 0xffff0000, v157
	v_pk_fma_f32 v[134:135], v[14:15], v[190:191], v[134:135]
	v_pk_fma_f32 v[150:151], v[16:17], v[188:189], v[150:151]
	v_cvt_pk_bf16_f32 v134, v134, v135
	v_cvt_pk_bf16_f32 v135, v150, v151
	global_store_dwordx2 v[146:147], v[134:135], off offset:256
	v_lshlrev_b32_e32 v134, 16, v152
	v_and_b32_e32 v135, 0xffff0000, v152
	v_lshlrev_b32_e32 v150, 16, v153
	v_and_b32_e32 v151, 0xffff0000, v153
	v_pk_fma_f32 v[134:135], v[10:11], v[130:131], v[134:135]
	v_pk_fma_f32 v[150:151], v[12:13], v[132:133], v[150:151]
	v_cvt_pk_bf16_f32 v134, v134, v135
	v_cvt_pk_bf16_f32 v135, v150, v151
	global_store_dwordx2 v[146:147], v[134:135], off offset:288
	v_lshlrev_b32_e32 v134, 16, v148
	v_and_b32_e32 v135, 0xffff0000, v148
	v_lshlrev_b32_e32 v146, 16, v149
	v_and_b32_e32 v147, 0xffff0000, v149
	v_pk_fma_f32 v[134:135], v[6:7], v[190:191], v[134:135]
	v_pk_fma_f32 v[146:147], v[8:9], v[188:189], v[146:147]
	v_cvt_pk_bf16_f32 v134, v134, v135
	v_cvt_pk_bf16_f32 v135, v146, v147
	global_store_dwordx2 v[142:143], v[134:135], off offset:256
	v_lshlrev_b32_e32 v134, 16, v144
	v_and_b32_e32 v135, 0xffff0000, v144
	v_pk_fma_f32 v[134:135], v[2:3], v[130:131], v[134:135]
	v_lshlrev_b32_e32 v130, 16, v145
	v_and_b32_e32 v131, 0xffff0000, v145
	v_cvt_pk_bf16_f32 v0, v134, v135
	v_pk_fma_f32 v[130:131], v[4:5], v[132:133], v[130:131]
	global_store_dword v[142:143], v0, off offset:288
	v_mov_b32_e32 v252, 0x358637bd
	s_cbranch_execnz .LBB0_769
	s_branch .LBB0_779

; __device__ __forceinline__ float lo_bf(unsigned u) { return __uint_as_float(u << 16); }
; __device__ __forceinline__ float hi_bf(unsigned u) { return __uint_as_float(u & 0xffff0000u); }
; __device__ __forceinline__ int get_tid512() { int t = threadIdx.x; asm volatile("" : "+v"(t)); return t; }
; #define TILE_LOOP(MT, NT) for (int i_ = blockIdx.x >> 3, mx_ = (MT) >> 3, n4_ = 4 * (NT); i_ < mx_ * (NT); i_ += gridDim.x >> 3)
; __global__ void __launch_bounds__(512, 2) fwd_megakernel(Params p) {
;     ...
;         TILE_LOOP(288, 7) {
;           const int mt = TILE_MT(288, 7), nt = TILE_NT(7), m0 = mt * 256;
;           const bool isq = nt < 3;
;           const u16* A = isq ? ZA + 256 : ZA;
;           __syncthreads();
;           {
;             const int t5 = get_tid512(), row = t5 >> 1, hf = t5 & 1;
;             const u16* src = A + (size_t)(m0 + row) * 512 + hf * 128;
;             float ss = 0.f;
; #pragma unroll
;             for (int i = 0; i < 16; ++i) {
;               uint4 raw = *(const uint4*)(src + i * 8);
;               unsigned w[4] = {raw.x, raw.y, raw.z, raw.w};
; #pragma unroll
;               for (int k = 0; k < 4; ++k) { float a = lo_bf(w[k]), b = hi_bf(w[k]); ss += a * a + b * b; }
;             }
;             ss += __shfl_xor(ss, 1);
;             if (hf == 0) srstd[row] = rsqrtf(ss * (1.f / 256.f) + EPSV);
.LBB0_1390:
	s_bfe_u32 s0, s49, 0x60002
	s_mul_i32 s0, s0, 37
	s_bfe_u32 s0, s0, 0x80008
	s_lshl_b32 s1, s0, 2
	s_mul_i32 s0, s0, 28
	s_and_b32 s1, s1, 60
	s_sub_i32 s0, s49, s0
	s_add_i32 s1, s55, s1
	s_and_b32 s8, s0, 0xff
	s_and_b32 s0, s0, 3
	s_or_b32 s14, s1, s0
	s_lshl_b32 s50, s14, 8
	s_cmp_gt_u32 s8, 11
	v_mov_b32_e32 v0, v206
	s_cselect_b64 s[6:7], -1, 0
	s_cmp_lt_u32 s8, 12
	s_waitcnt lgkmcnt(0)
	s_barrier
	s_cselect_b32 s0, 0x200, 0
	v_ashrrev_i32_e32 v20, 1, v0
	s_waitcnt lgkmcnt(0)
	v_add_u32_e32 v2, s50, v20
	s_add_u32 s12, s70, s0
	v_ashrrev_i32_e32 v3, 31, v2
	s_addc_u32 s13, s71, 0
	v_and_b32_e32 v21, 1, v0
	v_lshlrev_b64 v[2:3], 10, v[2:3]
	v_lshl_add_u64 v[2:3], s[12:13], 0, v[2:3]
	v_lshlrev_b32_e32 v0, 8, v21
	v_lshl_add_u64 v[18:19], v[2:3], 0, v[0:1]
	global_load_dwordx4 v[2:5], v[18:19], off offset:48
	global_load_dwordx4 v[6:9], v[18:19], off offset:32
	global_load_dwordx4 v[10:13], v[18:19], off offset:16
	global_load_dwordx4 v[14:17], v[18:19], off
	global_load_dwordx4 v[64:67], v[18:19], off offset:112
	global_load_dwordx4 v[68:71], v[18:19], off offset:96
	global_load_dwordx4 v[72:75], v[18:19], off offset:80
	global_load_dwordx4 v[76:79], v[18:19], off offset:64
	global_load_dwordx4 v[80:83], v[18:19], off offset:176
	global_load_dwordx4 v[84:87], v[18:19], off offset:160
	global_load_dwordx4 v[88:91], v[18:19], off offset:144
	global_load_dwordx4 v[92:95], v[18:19], off offset:128
	global_load_dwordx4 v[96:99], v[18:19], off offset:240
	global_load_dwordx4 v[100:103], v[18:19], off offset:224
	global_load_dwordx4 v[104:107], v[18:19], off offset:208
	global_load_dwordx4 v[108:111], v[18:19], off offset:192
	s_waitcnt vmcnt(0)
	v_lshlrev_b32_e32 v0, 16, v14
	v_and_b32_e32 v14, 0xffff0000, v14
	v_mul_f32_e32 v14, v14, v14
	v_fmac_f32_e32 v14, v0, v0
	v_lshlrev_b32_e32 v0, 16, v15
	v_and_b32_e32 v15, 0xffff0000, v15
	v_mul_f32_e32 v15, v15, v15
	v_fmac_f32_e32 v15, v0, v0
	v_add_f32_e32 v0, v14, v15
	v_and_b32_e32 v15, 0xffff0000, v16
	v_lshlrev_b32_e32 v14, 16, v16
	v_mul_f32_e32 v15, v15, v15
	v_fmac_f32_e32 v15, v14, v14
	v_add_f32_e32 v0, v0, v15
	v_and_b32_e32 v15, 0xffff0000, v17
	v_lshlrev_b32_e32 v14, 16, v17
	v_mul_f32_e32 v15, v15, v15
	v_fmac_f32_e32 v15, v14, v14
	v_lshlrev_b32_e32 v14, 16, v10
	v_and_b32_e32 v10, 0xffff0000, v10
	v_mul_f32_e32 v10, v10, v10
	v_add_f32_e32 v0, v0, v15
	v_fmac_f32_e32 v10, v14, v14
	v_add_f32_e32 v0, v0, v10
	v_lshlrev_b32_e32 v10, 16, v11
	v_and_b32_e32 v11, 0xffff0000, v11
	v_mul_f32_e32 v11, v11, v11
	v_fmac_f32_e32 v11, v10, v10
	v_add_f32_e32 v0, v0, v11
	v_and_b32_e32 v11, 0xffff0000, v12
	v_lshlrev_b32_e32 v10, 16, v12
	v_mul_f32_e32 v11, v11, v11
	v_fmac_f32_e32 v11, v10, v10
	v_add_f32_e32 v0, v0, v11
	v_and_b32_e32 v11, 0xffff0000, v13
	v_lshlrev_b32_e32 v10, 16, v13
	v_mul_f32_e32 v11, v11, v11
	v_fmac_f32_e32 v11, v10, v10
	v_lshlrev_b32_e32 v10, 16, v6
	v_and_b32_e32 v6, 0xffff0000, v6
	v_mul_f32_e32 v6, v6, v6
	v_add_f32_e32 v0, v0, v11
	v_fmac_f32_e32 v6, v10, v10
	v_add_f32_e32 v0, v0, v6
	v_lshlrev_b32_e32 v6, 16, v7
	v_and_b32_e32 v7, 0xffff0000, v7
	v_mul_f32_e32 v7, v7, v7
	v_fmac_f32_e32 v7, v6, v6
	v_add_f32_e32 v0, v0, v7
	v_and_b32_e32 v7, 0xffff0000, v8
	v_lshlrev_b32_e32 v6, 16, v8
	v_mul_f32_e32 v7, v7, v7
	v_fmac_f32_e32 v7, v6, v6
	v_add_f32_e32 v0, v0, v7
	v_and_b32_e32 v7, 0xffff0000, v9
	v_lshlrev_b32_e32 v6, 16, v9
	v_mul_f32_e32 v7, v7, v7
	v_fmac_f32_e32 v7, v6, v6
	v_lshlrev_b32_e32 v6, 16, v2
	v_and_b32_e32 v2, 0xffff0000, v2
	v_mul_f32_e32 v2, v2, v2
	v_add_f32_e32 v0, v0, v7
	v_fmac_f32_e32 v2, v6, v6
	v_add_f32_e32 v0, v0, v2
	v_lshlrev_b32_e32 v2, 16, v3
	v_and_b32_e32 v3, 0xffff0000, v3
	v_mul_f32_e32 v3, v3, v3
	v_fmac_f32_e32 v3, v2, v2
	v_add_f32_e32 v0, v0, v3
	v_and_b32_e32 v3, 0xffff0000, v4
	v_lshlrev_b32_e32 v2, 16, v4
	v_mul_f32_e32 v3, v3, v3
	v_fmac_f32_e32 v3, v2, v2
	v_add_f32_e32 v0, v0, v3
	v_and_b32_e32 v3, 0xffff0000, v5
	v_lshlrev_b32_e32 v2, 16, v5
	v_mul_f32_e32 v3, v3, v3
	v_fmac_f32_e32 v3, v2, v2
	v_add_f32_e32 v0, v0, v3
	v_mov_b32_e32 v2, v64
	v_mov_b32_e32 v3, v65
	v_mov_b32_e32 v4, v66
	v_mov_b32_e32 v5, v67
	v_mov_b32_e32 v6, v68
	v_mov_b32_e32 v7, v69
	v_mov_b32_e32 v8, v70
	v_mov_b32_e32 v9, v71
	v_mov_b32_e32 v10, v72
	v_mov_b32_e32 v11, v73
	v_mov_b32_e32 v12, v74
	v_mov_b32_e32 v13, v75
	v_mov_b32_e32 v14, v76
	v_mov_b32_e32 v15, v77
	v_mov_b32_e32 v16, v78
	v_mov_b32_e32 v17, v79
	v_lshlrev_b32_e32 v22, 16, v14
	v_and_b32_e32 v14, 0xffff0000, v14
	v_mul_f32_e32 v14, v14, v14
	v_fmac_f32_e32 v14, v22, v22
	v_add_f32_e32 v0, v0, v14
	v_lshlrev_b32_e32 v14, 16, v15
	v_and_b32_e32 v15, 0xffff0000, v15
	v_mul_f32_e32 v15, v15, v15
	v_fmac_f32_e32 v15, v14, v14
	v_add_f32_e32 v0, v0, v15
	v_and_b32_e32 v15, 0xffff0000, v16
	v_lshlrev_b32_e32 v14, 16, v16
	v_mul_f32_e32 v15, v15, v15
	v_fmac_f32_e32 v15, v14, v14
	v_add_f32_e32 v0, v0, v15
	v_and_b32_e32 v15, 0xffff0000, v17
	v_lshlrev_b32_e32 v14, 16, v17
	v_mul_f32_e32 v15, v15, v15
	v_fmac_f32_e32 v15, v14, v14
	v_lshlrev_b32_e32 v14, 16, v10
	v_and_b32_e32 v10, 0xffff0000, v10
	v_mul_f32_e32 v10, v10, v10
	v_add_f32_e32 v0, v0, v15
	v_fmac_f32_e32 v10, v14, v14
	v_add_f32_e32 v0, v0, v10
	v_lshlrev_b32_e32 v10, 16, v11
	v_and_b32_e32 v11, 0xffff0000, v11
	v_mul_f32_e32 v11, v11, v11
	v_fmac_f32_e32 v11, v10, v10
	v_add_f32_e32 v0, v0, v11
	v_and_b32_e32 v11, 0xffff0000, v12
	v_lshlrev_b32_e32 v10, 16, v12
	v_mul_f32_e32 v11, v11, v11
	v_fmac_f32_e32 v11, v10, v10
	v_add_f32_e32 v0, v0, v11
	v_and_b32_e32 v11, 0xffff0000, v13
	v_lshlrev_b32_e32 v10, 16, v13
	v_mul_f32_e32 v11, v11, v11
	v_fmac_f32_e32 v11, v10, v10
	v_lshlrev_b32_e32 v10, 16, v6
; __device__ __forceinline__ float lo_bf(unsigned u) { return __uint_as_float(u << 16); }
; __device__ __forceinline__ float hi_bf(unsigned u) { return __uint_as_float(u & 0xffff0000u); }
; __global__ void __launch_bounds__(512, 2) fwd_megakernel(Params p) {
;     ...
;             for (int i = 0; i < 16; ++i) {
;               uint4 raw = *(const uint4*)(src + i * 8);
;               unsigned w[4] = {raw.x, raw.y, raw.z, raw.w};
; #pragma unroll
;               for (int k = 0; k < 4; ++k) { float a = lo_bf(w[k]), b = hi_bf(w[k]); ss += a * a + b * b; }
;             }
;             ss += __shfl_xor(ss, 1);
	v_and_b32_e32 v6, 0xffff0000, v6
	v_mul_f32_e32 v6, v6, v6
	v_add_f32_e32 v0, v0, v11
	v_fmac_f32_e32 v6, v10, v10
	v_add_f32_e32 v0, v0, v6
	v_lshlrev_b32_e32 v6, 16, v7
	v_and_b32_e32 v7, 0xffff0000, v7
	v_mul_f32_e32 v7, v7, v7
	v_fmac_f32_e32 v7, v6, v6
	v_add_f32_e32 v0, v0, v7
	v_and_b32_e32 v7, 0xffff0000, v8
	v_lshlrev_b32_e32 v6, 16, v8
	v_mul_f32_e32 v7, v7, v7
	v_fmac_f32_e32 v7, v6, v6
	v_add_f32_e32 v0, v0, v7
	v_and_b32_e32 v7, 0xffff0000, v9
	v_lshlrev_b32_e32 v6, 16, v9
	v_mul_f32_e32 v7, v7, v7
	v_fmac_f32_e32 v7, v6, v6
	v_lshlrev_b32_e32 v6, 16, v2
	v_and_b32_e32 v2, 0xffff0000, v2
	v_mul_f32_e32 v2, v2, v2
	v_add_f32_e32 v0, v0, v7
	v_fmac_f32_e32 v2, v6, v6
	v_add_f32_e32 v0, v0, v2
	v_lshlrev_b32_e32 v2, 16, v3
	v_and_b32_e32 v3, 0xffff0000, v3
	v_mul_f32_e32 v3, v3, v3
	v_fmac_f32_e32 v3, v2, v2
	v_add_f32_e32 v0, v0, v3
	v_and_b32_e32 v3, 0xffff0000, v4
	v_lshlrev_b32_e32 v2, 16, v4
	v_mul_f32_e32 v3, v3, v3
	v_fmac_f32_e32 v3, v2, v2
	v_add_f32_e32 v0, v0, v3
	v_and_b32_e32 v3, 0xffff0000, v5
	v_lshlrev_b32_e32 v2, 16, v5
	v_mul_f32_e32 v3, v3, v3
	v_fmac_f32_e32 v3, v2, v2
	v_add_f32_e32 v0, v0, v3
	v_mov_b32_e32 v2, v80
	v_mov_b32_e32 v3, v81
	v_mov_b32_e32 v4, v82
	v_mov_b32_e32 v5, v83
	v_mov_b32_e32 v6, v84
	v_mov_b32_e32 v7, v85
	v_mov_b32_e32 v8, v86
	v_mov_b32_e32 v9, v87
	v_mov_b32_e32 v10, v88
	v_mov_b32_e32 v11, v89
	v_mov_b32_e32 v12, v90
	v_mov_b32_e32 v13, v91
	v_mov_b32_e32 v14, v92
	v_mov_b32_e32 v15, v93
	v_mov_b32_e32 v16, v94
	v_mov_b32_e32 v17, v95
	v_lshlrev_b32_e32 v22, 16, v14
	v_and_b32_e32 v14, 0xffff0000, v14
	v_mul_f32_e32 v14, v14, v14
	v_fmac_f32_e32 v14, v22, v22
	v_add_f32_e32 v0, v0, v14
	v_lshlrev_b32_e32 v14, 16, v15
	v_and_b32_e32 v15, 0xffff0000, v15
	v_mul_f32_e32 v15, v15, v15
	v_fmac_f32_e32 v15, v14, v14
	v_add_f32_e32 v0, v0, v15
	v_and_b32_e32 v15, 0xffff0000, v16
	v_lshlrev_b32_e32 v14, 16, v16
	v_mul_f32_e32 v15, v15, v15
	v_fmac_f32_e32 v15, v14, v14
	v_add_f32_e32 v0, v0, v15
	v_and_b32_e32 v15, 0xffff0000, v17
	v_lshlrev_b32_e32 v14, 16, v17
	v_mul_f32_e32 v15, v15, v15
	v_fmac_f32_e32 v15, v14, v14
	v_lshlrev_b32_e32 v14, 16, v10
	v_and_b32_e32 v10, 0xffff0000, v10
	v_mul_f32_e32 v10, v10, v10
	v_add_f32_e32 v0, v0, v15
	v_fmac_f32_e32 v10, v14, v14
	v_add_f32_e32 v0, v0, v10
	v_lshlrev_b32_e32 v10, 16, v11
	v_and_b32_e32 v11, 0xffff0000, v11
	v_mul_f32_e32 v11, v11, v11
	v_fmac_f32_e32 v11, v10, v10
	v_add_f32_e32 v0, v0, v11
	v_and_b32_e32 v11, 0xffff0000, v12
	v_lshlrev_b32_e32 v10, 16, v12
	v_mul_f32_e32 v11, v11, v11
	v_fmac_f32_e32 v11, v10, v10
	v_add_f32_e32 v0, v0, v11
	v_and_b32_e32 v11, 0xffff0000, v13
	v_lshlrev_b32_e32 v10, 16, v13
	v_mul_f32_e32 v11, v11, v11
	v_fmac_f32_e32 v11, v10, v10
	v_lshlrev_b32_e32 v10, 16, v6
	v_and_b32_e32 v6, 0xffff0000, v6
	v_mul_f32_e32 v6, v6, v6
	v_add_f32_e32 v0, v0, v11
	v_fmac_f32_e32 v6, v10, v10
	v_add_f32_e32 v0, v0, v6
	v_lshlrev_b32_e32 v6, 16, v7
	v_and_b32_e32 v7, 0xffff0000, v7
	v_mul_f32_e32 v7, v7, v7
	v_fmac_f32_e32 v7, v6, v6
	v_add_f32_e32 v0, v0, v7
	v_and_b32_e32 v7, 0xffff0000, v8
	v_lshlrev_b32_e32 v6, 16, v8
	v_mul_f32_e32 v7, v7, v7
	v_fmac_f32_e32 v7, v6, v6
	v_add_f32_e32 v0, v0, v7
	v_and_b32_e32 v7, 0xffff0000, v9
	v_lshlrev_b32_e32 v6, 16, v9
	v_mul_f32_e32 v7, v7, v7
	v_fmac_f32_e32 v7, v6, v6
	v_lshlrev_b32_e32 v6, 16, v2
	v_and_b32_e32 v2, 0xffff0000, v2
	v_mul_f32_e32 v2, v2, v2
	v_add_f32_e32 v0, v0, v7
	v_fmac_f32_e32 v2, v6, v6
	v_add_f32_e32 v0, v0, v2
	v_lshlrev_b32_e32 v2, 16, v3
	v_and_b32_e32 v3, 0xffff0000, v3
	v_mul_f32_e32 v3, v3, v3
	v_fmac_f32_e32 v3, v2, v2
	v_add_f32_e32 v0, v0, v3
	v_and_b32_e32 v3, 0xffff0000, v4
	v_lshlrev_b32_e32 v2, 16, v4
	v_mul_f32_e32 v3, v3, v3
	v_fmac_f32_e32 v3, v2, v2
	v_add_f32_e32 v0, v0, v3
	v_and_b32_e32 v3, 0xffff0000, v5
	v_lshlrev_b32_e32 v2, 16, v5
	v_mul_f32_e32 v3, v3, v3
	v_fmac_f32_e32 v3, v2, v2
	v_add_f32_e32 v0, v0, v3
	v_mov_b32_e32 v2, v96
	v_mov_b32_e32 v3, v97
	v_mov_b32_e32 v4, v98
	v_mov_b32_e32 v5, v99
	v_mov_b32_e32 v6, v100
	v_mov_b32_e32 v7, v101
	v_mov_b32_e32 v8, v102
	v_mov_b32_e32 v9, v103
	v_mov_b32_e32 v10, v104
	v_mov_b32_e32 v11, v105
	v_mov_b32_e32 v12, v106
	v_mov_b32_e32 v13, v107
	v_mov_b32_e32 v14, v108
	v_mov_b32_e32 v15, v109
	v_mov_b32_e32 v16, v110
	v_mov_b32_e32 v17, v111
	v_lshlrev_b32_e32 v18, 16, v14
	v_and_b32_e32 v14, 0xffff0000, v14
	v_mul_f32_e32 v14, v14, v14
	v_fmac_f32_e32 v14, v18, v18
	v_add_f32_e32 v0, v0, v14
	v_lshlrev_b32_e32 v14, 16, v15
	v_and_b32_e32 v15, 0xffff0000, v15
	v_mul_f32_e32 v15, v15, v15
	v_fmac_f32_e32 v15, v14, v14
	v_add_f32_e32 v0, v0, v15
	v_and_b32_e32 v15, 0xffff0000, v16
	v_lshlrev_b32_e32 v14, 16, v16
	v_mul_f32_e32 v15, v15, v15
	v_fmac_f32_e32 v15, v14, v14
	v_add_f32_e32 v0, v0, v15
	v_and_b32_e32 v15, 0xffff0000, v17
	v_lshlrev_b32_e32 v14, 16, v17
	v_mul_f32_e32 v15, v15, v15
	v_fmac_f32_e32 v15, v14, v14
	v_lshlrev_b32_e32 v14, 16, v10
	v_and_b32_e32 v10, 0xffff0000, v10
	v_mul_f32_e32 v10, v10, v10
	v_add_f32_e32 v0, v0, v15
	v_fmac_f32_e32 v10, v14, v14
	v_add_f32_e32 v0, v0, v10
	v_lshlrev_b32_e32 v10, 16, v11
	v_and_b32_e32 v11, 0xffff0000, v11
	v_mul_f32_e32 v11, v11, v11
	v_fmac_f32_e32 v11, v10, v10
	v_add_f32_e32 v0, v0, v11
	v_and_b32_e32 v11, 0xffff0000, v12
	v_lshlrev_b32_e32 v10, 16, v12
	v_mul_f32_e32 v11, v11, v11
	v_fmac_f32_e32 v11, v10, v10
	v_add_f32_e32 v0, v0, v11
	v_and_b32_e32 v11, 0xffff0000, v13
	v_lshlrev_b32_e32 v10, 16, v13
	v_mul_f32_e32 v11, v11, v11
	v_fmac_f32_e32 v11, v10, v10
	v_lshlrev_b32_e32 v10, 16, v6
	v_and_b32_e32 v6, 0xffff0000, v6
	v_mul_f32_e32 v6, v6, v6
	v_add_f32_e32 v0, v0, v11
	v_fmac_f32_e32 v6, v10, v10
	v_add_f32_e32 v0, v0, v6
	v_lshlrev_b32_e32 v6, 16, v7
	v_and_b32_e32 v7, 0xffff0000, v7
	v_mul_f32_e32 v7, v7, v7
	v_fmac_f32_e32 v7, v6, v6
	v_add_f32_e32 v0, v0, v7
	v_and_b32_e32 v7, 0xffff0000, v8
	v_lshlrev_b32_e32 v6, 16, v8
	v_mul_f32_e32 v7, v7, v7
	v_fmac_f32_e32 v7, v6, v6
	v_add_f32_e32 v0, v0, v7
	v_and_b32_e32 v7, 0xffff0000, v9
	v_lshlrev_b32_e32 v6, 16, v9
	v_mul_f32_e32 v7, v7, v7
	v_fmac_f32_e32 v7, v6, v6
	v_lshlrev_b32_e32 v6, 16, v2
	v_and_b32_e32 v2, 0xffff0000, v2
	v_mul_f32_e32 v2, v2, v2
	v_add_f32_e32 v0, v0, v7
	v_fmac_f32_e32 v2, v6, v6
	v_add_f32_e32 v0, v0, v2
	v_lshlrev_b32_e32 v2, 16, v3
	v_and_b32_e32 v3, 0xffff0000, v3
	v_mul_f32_e32 v3, v3, v3
	v_fmac_f32_e32 v3, v2, v2
	v_add_f32_e32 v0, v0, v3
	v_and_b32_e32 v3, 0xffff0000, v4
	v_lshlrev_b32_e32 v2, 16, v4
	v_mul_f32_e32 v3, v3, v3
	v_fmac_f32_e32 v3, v2, v2
	v_add_f32_e32 v0, v0, v3
	v_and_b32_e32 v3, 0xffff0000, v5
	v_lshlrev_b32_e32 v2, 16, v5
	v_mul_f32_e32 v3, v3, v3
	v_fmac_f32_e32 v3, v2, v2
	v_xor_b32_e32 v2, 1, v197
	v_cmp_lt_i32_e32 vcc, v2, v198
	v_add_f32_e32 v0, v0, v3
	s_nop 0
	v_cndmask_b32_e32 v2, v197, v2, vcc
	v_lshlrev_b32_e32 v2, 2, v2
	ds_bpermute_b32 v2, v2, v0
	v_cmp_eq_u32_e32 vcc, 0, v21
	s_and_saveexec_b64 s[0:1], vcc
	s_cbranch_execz .LBB0_1392
; __global__ void __launch_bounds__(512, 2) fwd_megakernel(Params p) {
;     ...
;             ss += __shfl_xor(ss, 1);
;             if (hf == 0) srstd[row] = rsqrtf(ss * (1.f / 256.f) + EPSV);
	s_waitcnt lgkmcnt(0)
	v_add_f32_e32 v0, v0, v2
	v_fmamk_f32 v0, v0, 0x3b800000, v252
	v_mul_f32_e32 v2, 0x4b800000, v0
	v_cmp_gt_f32_e32 vcc, s90, v0
	s_nop 1
	v_cndmask_b32_e32 v0, v0, v2, vcc
	v_rsq_f32_e32 v0, v0
	s_nop 0
	v_mul_f32_e32 v2, 0x45800000, v0
	v_cndmask_b32_e32 v0, v0, v2, vcc
	v_lshl_add_u32 v2, v20, 2, v201
	ds_write_b32 v2, v0

; __device__ __forceinline__ float lo_bf(unsigned u) { return __uint_as_float(u << 16); }
; __device__ __forceinline__ float hi_bf(unsigned u) { return __uint_as_float(u & 0xffff0000u); }
; template <class Epi>
; __device__ __forceinline__ void gemm_tile(const u16* __restrict__ A, int lda, const u16* __restrict__ Wt, int K,
;                                           int m0, int n0, char* sbase, const Epi& epi) {
;     ...
;       for (int ai = 0; ai < 2; ++ai) {
;         float4 gg[2][2];
;         uint2 rr[2][4][2];
; #pragma unroll
;         for (int bj = 0; bj < 2; ++bj)
; #pragma unroll
;           for (int n = 0; n < 2; ++n) gg[bj][n] = epi.loadG(m0, n0 + bj * 128 + wc * 32 + n * 16 + fq * 4);
; #pragma unroll
;         for (int bj = 0; bj < 2; ++bj)
; #pragma unroll
;           for (int m = 0; m < 4; ++m)
; #pragma unroll
;             for (int n = 0; n < 2; ++n)
;               rr[bj][m][n] = epi.loadR(m0 + ai * 128 + wr * 64 + m * 16 + fr, n0 + bj * 128 + wc * 32 + n * 16 + fq * 4);
; #pragma unroll
;         for (int bj = 0; bj < 2; ++bj)
; #pragma unroll
;           for (int m = 0; m < 4; ++m)
; #pragma unroll
;             for (int n = 0; n < 2; ++n)
;               epi.apply(m0 + ai * 128 + wr * 64 + m * 16 + fr, n0 + bj * 128 + wc * 32 + n * 16 + fq * 4, acc[ai][bj][m][n],
;                         rr[bj][m][n], gg[bj][n]);
;   __device__ __forceinline__ float4 loadG(int m, int n) const { return *(const float4*)(gate + (size_t)modrow(m) * 6144 + n); }
;   __device__ __forceinline__ void apply(int m, int n, f32x4 v, uint2 a, float4 g) const {
;     f32x4 o;
;     o[0] = lo_bf(a.x) + mul * g.x * v[0]; o[1] = hi_bf(a.x) + mul * g.y * v[1];
;     o[2] = lo_bf(a.y) + mul * g.z * v[2]; o[3] = hi_bf(a.y) + mul * g.w * v[3];
;     store4bf(p->Rb + (size_t)m * 1024 + n, o);
.LBB0_1624:
	s_andn2_b64 vcc, exec, s[0:1]
	s_cbranch_vccnz .LBB0_1615
	v_ashrrev_i32_e32 v133, 31, v132
	s_min_u32 s0, s14, 0x10000
	v_or_b32_e32 v134, 48, v132
	v_lshlrev_b64 v[136:137], 11, v[132:133]
	v_or_b32_e32 v138, 16, v132
	v_or_b32_e32 v132, 32, v132
	s_lshr_b32 s0, s0, 11
	v_ashrrev_i32_e32 v135, 31, v134
	v_ashrrev_i32_e32 v139, 31, v138
	v_ashrrev_i32_e32 v133, 31, v132
	s_mulk_i32 s0, 0x6000
	v_lshlrev_b64 v[134:135], 11, v[134:135]
	v_lshlrev_b64 v[138:139], 11, v[138:139]
	v_lshlrev_b64 v[132:133], 11, v[132:133]
	s_add_u32 s14, s6, s0
	v_lshl_add_u64 v[134:135], s[38:39], 0, v[134:135]
	v_lshl_add_u64 v[136:137], s[38:39], 0, v[136:137]
	v_lshlrev_b32_e32 v0, 1, v162
	v_lshl_add_u64 v[138:139], s[38:39], 0, v[138:139]
	v_lshl_add_u64 v[132:133], s[38:39], 0, v[132:133]
	s_addc_u32 s15, s7, 0
	v_lshlrev_b32_e32 v158, 2, v162
	v_lshl_add_u64 v[136:137], v[136:137], 0, v[0:1]
	v_lshl_add_u64 v[146:147], v[138:139], 0, v[0:1]
	v_lshl_add_u64 v[140:141], v[132:133], 0, v[0:1]
	v_lshl_add_u64 v[132:133], v[134:135], 0, v[0:1]
	global_load_dwordx2 v[164:165], v[136:137], off
	global_load_dwordx2 v[166:167], v[136:137], off offset:32
	global_load_dwordx2 v[168:169], v[146:147], off
	global_load_dwordx2 v[170:171], v[146:147], off offset:32
	global_load_dwordx2 v[172:173], v[140:141], off
	global_load_dwordx2 v[174:175], v[140:141], off offset:32
	global_load_dwordx2 v[134:135], v[132:133], off
	global_load_dwordx2 v[176:177], v[132:133], off offset:32
	global_load_dwordx2 v[156:157], v[136:137], off offset:256
	global_load_dwordx2 v[154:155], v[136:137], off offset:288
	global_load_dwordx2 v[152:153], v[146:147], off offset:256
	global_load_dwordx2 v[150:151], v[146:147], off offset:288
	global_load_dwordx2 v[148:149], v[140:141], off offset:256
	global_load_dwordx2 v[144:145], v[140:141], off offset:288
	global_load_dwordx2 v[142:143], v[132:133], off offset:256
	global_load_dwordx2 v[138:139], v[132:133], off offset:288
	global_load_dwordx4 v[160:163], v158, s[14:15]
	global_load_dwordx4 v[208:211], v158, s[14:15]
	global_load_dwordx4 v[212:215], v158, s[14:15] offset:64
	global_load_dwordx4 v[216:219], v158, s[14:15] offset:512
	global_load_dwordx4 v[220:223], v158, s[14:15] offset:576
	s_mov_b64 s[0:1], 0x40000
	s_waitcnt vmcnt(0)
	v_lshlrev_b32_e32 v178, 16, v164
	v_and_b32_e32 v179, 0xffff0000, v164
	v_pk_mul_f32 v[180:181], v[130:131], v[160:161]
	v_lshlrev_b32_e32 v160, 16, v165
	v_and_b32_e32 v161, 0xffff0000, v165
	v_pk_mul_f32 v[164:165], v[130:131], v[162:163]
	v_pk_fma_f32 v[126:127], v[126:127], v[180:181], v[178:179]
	v_pk_fma_f32 v[128:129], v[128:129], v[164:165], v[160:161]
	v_mov_b32_e32 v160, v212
	v_mov_b32_e32 v161, v213
	v_mov_b32_e32 v162, v214
	v_mov_b32_e32 v163, v215
	v_cvt_pk_bf16_f32 v126, v126, v127
	v_cvt_pk_bf16_f32 v127, v128, v129
	v_lshlrev_b32_e32 v128, 16, v166
	v_and_b32_e32 v129, 0xffff0000, v166
	v_pk_mul_f32 v[160:161], v[130:131], v[160:161]
	s_nop 0
	v_pk_fma_f32 v[122:123], v[122:123], v[160:161], v[128:129]
	v_lshlrev_b32_e32 v128, 16, v167
	v_and_b32_e32 v129, 0xffff0000, v167
	v_pk_mul_f32 v[162:163], v[130:131], v[162:163]
	v_cvt_pk_bf16_f32 v122, v122, v123
	v_pk_fma_f32 v[124:125], v[124:125], v[162:163], v[128:129]
	s_nop 0
	v_cvt_pk_bf16_f32 v123, v124, v125
	v_lshlrev_b32_e32 v124, 16, v168
	v_and_b32_e32 v125, 0xffff0000, v168
	v_pk_fma_f32 v[118:119], v[118:119], v[180:181], v[124:125]
	v_lshlrev_b32_e32 v124, 16, v169
	v_and_b32_e32 v125, 0xffff0000, v169
	v_pk_fma_f32 v[120:121], v[120:121], v[164:165], v[124:125]
	v_cvt_pk_bf16_f32 v118, v118, v119
	v_cvt_pk_bf16_f32 v119, v120, v121
	v_lshlrev_b32_e32 v120, 16, v170
	v_and_b32_e32 v121, 0xffff0000, v170
	v_pk_fma_f32 v[114:115], v[114:115], v[160:161], v[120:121]
	v_lshlrev_b32_e32 v120, 16, v171
	v_and_b32_e32 v121, 0xffff0000, v171
	v_pk_fma_f32 v[116:117], v[116:117], v[162:163], v[120:121]
	v_cvt_pk_bf16_f32 v114, v114, v115
	v_cvt_pk_bf16_f32 v115, v116, v117
	v_lshlrev_b32_e32 v116, 16, v172
	v_and_b32_e32 v117, 0xffff0000, v172
	v_pk_fma_f32 v[110:111], v[110:111], v[180:181], v[116:117]
	v_lshlrev_b32_e32 v116, 16, v173
	v_and_b32_e32 v117, 0xffff0000, v173
	v_pk_fma_f32 v[112:113], v[112:113], v[164:165], v[116:117]
	v_cvt_pk_bf16_f32 v110, v110, v111
	v_cvt_pk_bf16_f32 v111, v112, v113
	v_lshlrev_b32_e32 v112, 16, v174
	v_and_b32_e32 v113, 0xffff0000, v174
	v_pk_fma_f32 v[106:107], v[106:107], v[160:161], v[112:113]
	v_lshlrev_b32_e32 v112, 16, v175
	v_and_b32_e32 v113, 0xffff0000, v175
	v_pk_fma_f32 v[108:109], v[108:109], v[162:163], v[112:113]
	v_cvt_pk_bf16_f32 v106, v106, v107
	v_cvt_pk_bf16_f32 v107, v108, v109
	v_lshlrev_b32_e32 v108, 16, v134
	v_and_b32_e32 v109, 0xffff0000, v134
	v_pk_fma_f32 v[102:103], v[102:103], v[180:181], v[108:109]
	v_lshlrev_b32_e32 v108, 16, v135
	v_and_b32_e32 v109, 0xffff0000, v135
	v_pk_fma_f32 v[104:105], v[104:105], v[164:165], v[108:109]
	v_cvt_pk_bf16_f32 v102, v102, v103
	v_cvt_pk_bf16_f32 v103, v104, v105
	v_lshlrev_b32_e32 v104, 16, v176
	v_and_b32_e32 v105, 0xffff0000, v176
	v_pk_fma_f32 v[98:99], v[98:99], v[160:161], v[104:105]
	v_lshlrev_b32_e32 v104, 16, v177
	v_and_b32_e32 v105, 0xffff0000, v177
	v_pk_fma_f32 v[100:101], v[100:101], v[162:163], v[104:105]
	v_mov_b32_e32 v160, v216
	v_mov_b32_e32 v161, v217
	v_mov_b32_e32 v162, v218
	v_mov_b32_e32 v163, v219
	v_cvt_pk_bf16_f32 v98, v98, v99
	v_cvt_pk_bf16_f32 v99, v100, v101
	v_lshlrev_b32_e32 v100, 16, v156
	v_and_b32_e32 v101, 0xffff0000, v156
	v_lshlrev_b32_e32 v108, 16, v157
	v_and_b32_e32 v109, 0xffff0000, v157
	v_lshlrev_b32_e32 v112, 16, v154
	v_and_b32_e32 v113, 0xffff0000, v154
; __device__ __forceinline__ float lo_bf(unsigned u) { return __uint_as_float(u << 16); }
; __device__ __forceinline__ float hi_bf(unsigned u) { return __uint_as_float(u & 0xffff0000u); }
; template <class Epi>
; __device__ __forceinline__ void gemm_tile(const u16* __restrict__ A, int lda, const u16* __restrict__ Wt, int K,
;                                           int m0, int n0, char* sbase, const Epi& epi) {
;     ...
;       for (int ai = 0; ai < 2; ++ai) {
;         float4 gg[2][2];
;         uint2 rr[2][4][2];
; #pragma unroll
;         for (int bj = 0; bj < 2; ++bj)
; #pragma unroll
;           for (int n = 0; n < 2; ++n) gg[bj][n] = epi.loadG(m0, n0 + bj * 128 + wc * 32 + n * 16 + fq * 4);
; #pragma unroll
;         for (int bj = 0; bj < 2; ++bj)
; #pragma unroll
;           for (int m = 0; m < 4; ++m)
; #pragma unroll
;             for (int n = 0; n < 2; ++n)
;               rr[bj][m][n] = epi.loadR(m0 + ai * 128 + wr * 64 + m * 16 + fr, n0 + bj * 128 + wc * 32 + n * 16 + fq * 4);
; #pragma unroll
;         for (int bj = 0; bj < 2; ++bj)
; #pragma unroll
;           for (int m = 0; m < 4; ++m)
; #pragma unroll
;             for (int n = 0; n < 2; ++n)
;               epi.apply(m0 + ai * 128 + wr * 64 + m * 16 + fr, n0 + bj * 128 + wc * 32 + n * 16 + fq * 4, acc[ai][bj][m][n],
;                         rr[bj][m][n], gg[bj][n]);
;   __device__ __forceinline__ float4 loadG(int m, int n) const { return *(const float4*)(gate + (size_t)modrow(m) * 6144 + n); }
;   __device__ __forceinline__ void apply(int m, int n, f32x4 v, uint2 a, float4 g) const {
;     f32x4 o;
;     o[0] = lo_bf(a.x) + mul * g.x * v[0]; o[1] = hi_bf(a.x) + mul * g.y * v[1];
;     o[2] = lo_bf(a.y) + mul * g.z * v[2]; o[3] = hi_bf(a.y) + mul * g.w * v[3];
;     store4bf(p->Rb + (size_t)m * 1024 + n, o);
	v_pk_mul_f32 v[104:105], v[130:131], v[160:161]
	s_nop 0
	v_pk_fma_f32 v[94:95], v[94:95], v[104:105], v[100:101]
	v_pk_mul_f32 v[100:101], v[130:131], v[162:163]
	s_nop 0
	v_pk_fma_f32 v[96:97], v[96:97], v[100:101], v[108:109]
	v_cvt_pk_bf16_f32 v108, v94, v95
	v_cvt_pk_bf16_f32 v109, v96, v97
	v_mov_b32_e32 v94, v220
	v_mov_b32_e32 v95, v221
	v_mov_b32_e32 v96, v222
	v_mov_b32_e32 v97, v223
	s_nop 0
	global_store_dwordx2 v[136:137], v[126:127], off
	global_store_dwordx2 v[136:137], v[122:123], off offset:32
	global_store_dwordx2 v[146:147], v[118:119], off
	global_store_dwordx2 v[146:147], v[114:115], off offset:32
	global_store_dwordx2 v[140:141], v[110:111], off
	global_store_dwordx2 v[140:141], v[106:107], off offset:32
	global_store_dwordx2 v[132:133], v[102:103], off
	global_store_dwordx2 v[132:133], v[98:99], off offset:32
	global_store_dwordx2 v[136:137], v[108:109], off offset:256
	v_pk_mul_f32 v[94:95], v[130:131], v[94:95]
	s_nop 0
	v_pk_fma_f32 v[90:91], v[90:91], v[94:95], v[112:113]
	v_lshlrev_b32_e32 v112, 16, v155
	v_and_b32_e32 v113, 0xffff0000, v155
	v_pk_mul_f32 v[96:97], v[130:131], v[96:97]
	v_cvt_pk_bf16_f32 v90, v90, v91
	v_pk_fma_f32 v[92:93], v[92:93], v[96:97], v[112:113]
	s_nop 0
	v_cvt_pk_bf16_f32 v91, v92, v93
	global_store_dwordx2 v[136:137], v[90:91], off offset:288
	v_lshlrev_b32_e32 v90, 16, v152
	v_and_b32_e32 v91, 0xffff0000, v152
	v_pk_fma_f32 v[86:87], v[86:87], v[104:105], v[90:91]
	v_lshlrev_b32_e32 v90, 16, v153
	v_and_b32_e32 v91, 0xffff0000, v153
	v_pk_fma_f32 v[88:89], v[88:89], v[100:101], v[90:91]
	v_cvt_pk_bf16_f32 v86, v86, v87
	v_cvt_pk_bf16_f32 v87, v88, v89
	global_store_dwordx2 v[146:147], v[86:87], off offset:256
	v_lshlrev_b32_e32 v86, 16, v150
	v_and_b32_e32 v87, 0xffff0000, v150
	v_pk_fma_f32 v[82:83], v[82:83], v[94:95], v[86:87]
	v_lshlrev_b32_e32 v86, 16, v151
	v_and_b32_e32 v87, 0xffff0000, v151
	v_pk_fma_f32 v[84:85], v[84:85], v[96:97], v[86:87]
	v_cvt_pk_bf16_f32 v82, v82, v83
	v_cvt_pk_bf16_f32 v83, v84, v85
	global_store_dwordx2 v[146:147], v[82:83], off offset:288
	v_lshlrev_b32_e32 v82, 16, v148
	v_and_b32_e32 v83, 0xffff0000, v148
	v_pk_fma_f32 v[78:79], v[78:79], v[104:105], v[82:83]
	v_lshlrev_b32_e32 v82, 16, v149
	v_and_b32_e32 v83, 0xffff0000, v149
	v_pk_fma_f32 v[80:81], v[80:81], v[100:101], v[82:83]
	v_cvt_pk_bf16_f32 v78, v78, v79
	v_cvt_pk_bf16_f32 v79, v80, v81
	global_store_dwordx2 v[140:141], v[78:79], off offset:256
	v_lshlrev_b32_e32 v78, 16, v144
	v_and_b32_e32 v79, 0xffff0000, v144
	v_pk_fma_f32 v[74:75], v[74:75], v[94:95], v[78:79]
	v_lshlrev_b32_e32 v78, 16, v145
	v_and_b32_e32 v79, 0xffff0000, v145
	v_pk_fma_f32 v[76:77], v[76:77], v[96:97], v[78:79]
	v_cvt_pk_bf16_f32 v74, v74, v75
	v_cvt_pk_bf16_f32 v75, v76, v77
	global_store_dwordx2 v[140:141], v[74:75], off offset:288
	v_lshlrev_b32_e32 v74, 16, v142
	v_and_b32_e32 v75, 0xffff0000, v142
	v_pk_fma_f32 v[70:71], v[70:71], v[104:105], v[74:75]
	v_lshlrev_b32_e32 v74, 16, v143
	v_and_b32_e32 v75, 0xffff0000, v143
	v_pk_fma_f32 v[72:73], v[72:73], v[100:101], v[74:75]
	v_lshl_add_u64 v[78:79], v[136:137], 0, s[0:1]
	s_mov_b32 s0, 0x40000
	v_cvt_pk_bf16_f32 v70, v70, v71
	v_cvt_pk_bf16_f32 v71, v72, v73
	v_add_co_u32_e32 v86, vcc, s0, v136
	global_store_dwordx2 v[132:133], v[70:71], off offset:256
	v_lshlrev_b32_e32 v70, 16, v138
	v_and_b32_e32 v71, 0xffff0000, v138
	v_addc_co_u32_e32 v87, vcc, 0, v137, vcc
	s_mov_b32 s0, 0x48000
	v_pk_fma_f32 v[66:67], v[66:67], v[94:95], v[70:71]
	v_lshlrev_b32_e32 v70, 16, v139
	v_and_b32_e32 v71, 0xffff0000, v139
	v_add_co_u32_e32 v88, vcc, s0, v136
	s_mov_b64 s[0:1], 0x50000
	v_pk_fma_f32 v[68:69], v[68:69], v[96:97], v[70:71]
	v_addc_co_u32_e32 v89, vcc, 0, v137, vcc
	v_lshl_add_u64 v[70:71], v[136:137], 0, s[0:1]
	s_mov_b32 s0, 0x50000
	v_cvt_pk_bf16_f32 v66, v66, v67
	v_cvt_pk_bf16_f32 v67, v68, v69
	v_add_co_u32_e32 v90, vcc, s0, v136
	s_mov_b64 s[0:1], 0x58000
	global_store_dwordx2 v[132:133], v[66:67], off offset:288
	v_addc_co_u32_e32 v91, vcc, 0, v137, vcc
	v_lshl_add_u64 v[66:67], v[136:137], 0, s[0:1]
	s_mov_b32 s0, 0x58000
	v_add_co_u32_e32 v92, vcc, s0, v136
	global_load_dwordx2 v[104:105], v[86:87], off
	global_load_dwordx2 v[106:107], v[78:79], off offset:32
	v_addc_co_u32_e32 v93, vcc, 0, v137, vcc
	v_lshl_add_u64 v[74:75], v[136:137], 0, s[28:29]
	global_load_dwordx2 v[108:109], v[88:89], off
	global_load_dwordx2 v[110:111], v[74:75], off offset:32
	global_load_dwordx2 v[112:113], v[90:91], off
	global_load_dwordx2 v[114:115], v[70:71], off offset:32
	global_load_dwordx2 v[116:117], v[92:93], off
	global_load_dwordx2 v[98:99], v[66:67], off offset:32
	global_load_dwordx2 v[96:97], v[78:79], off offset:256
	global_load_dwordx2 v[94:95], v[78:79], off offset:288
	global_load_dwordx2 v[84:85], v[74:75], off offset:256
	global_load_dwordx2 v[82:83], v[74:75], off offset:288
	global_load_dwordx2 v[80:81], v[70:71], off offset:256
	global_load_dwordx2 v[76:77], v[70:71], off offset:288
	global_load_dwordx2 v[72:73], v[66:67], off offset:256
	v_mov_b32_e32 v100, v208
	v_mov_b32_e32 v101, v209
	v_mov_b32_e32 v102, v210
	v_mov_b32_e32 v103, v211
	global_load_dwordx2 v[68:69], v[66:67], off offset:288
	s_mov_b64 s[0:1], 0x120
	v_lshl_add_u64 v[136:137], v[66:67], 0, s[0:1]
	s_waitcnt vmcnt(0)
; __device__ __forceinline__ float lo_bf(unsigned u) { return __uint_as_float(u << 16); }
; __device__ __forceinline__ float hi_bf(unsigned u) { return __uint_as_float(u & 0xffff0000u); }
; template <class Epi>
; __device__ __forceinline__ void gemm_tile(const u16* __restrict__ A, int lda, const u16* __restrict__ Wt, int K,
;                                           int m0, int n0, char* sbase, const Epi& epi) {
;     ...
;       for (int ai = 0; ai < 2; ++ai) {
;         float4 gg[2][2];
;         uint2 rr[2][4][2];
; #pragma unroll
;         for (int bj = 0; bj < 2; ++bj)
; #pragma unroll
;           for (int n = 0; n < 2; ++n) gg[bj][n] = epi.loadG(m0, n0 + bj * 128 + wc * 32 + n * 16 + fq * 4);
; #pragma unroll
;         for (int bj = 0; bj < 2; ++bj)
; #pragma unroll
;           for (int m = 0; m < 4; ++m)
; #pragma unroll
;             for (int n = 0; n < 2; ++n)
;               rr[bj][m][n] = epi.loadR(m0 + ai * 128 + wr * 64 + m * 16 + fr, n0 + bj * 128 + wc * 32 + n * 16 + fq * 4);
; #pragma unroll
;         for (int bj = 0; bj < 2; ++bj)
; #pragma unroll
;           for (int m = 0; m < 4; ++m)
; #pragma unroll
;             for (int n = 0; n < 2; ++n)
;               epi.apply(m0 + ai * 128 + wr * 64 + m * 16 + fr, n0 + bj * 128 + wc * 32 + n * 16 + fq * 4, acc[ai][bj][m][n],
;                         rr[bj][m][n], gg[bj][n]);
;   __device__ __forceinline__ float4 loadG(int m, int n) const { return *(const float4*)(gate + (size_t)modrow(m) * 6144 + n); }
;   __device__ __forceinline__ void apply(int m, int n, f32x4 v, uint2 a, float4 g) const {
;     f32x4 o;
;     o[0] = lo_bf(a.x) + mul * g.x * v[0]; o[1] = hi_bf(a.x) + mul * g.y * v[1];
;     o[2] = lo_bf(a.y) + mul * g.z * v[2]; o[3] = hi_bf(a.y) + mul * g.w * v[3];
;     store4bf(p->Rb + (size_t)m * 1024 + n, o);
	v_lshlrev_b32_e32 v118, 16, v104
	v_and_b32_e32 v119, 0xffff0000, v104
	v_pk_mul_f32 v[120:121], v[130:131], v[100:101]
	v_lshlrev_b32_e32 v100, 16, v105
	v_and_b32_e32 v101, 0xffff0000, v105
	v_pk_mul_f32 v[104:105], v[130:131], v[102:103]
	v_pk_fma_f32 v[62:63], v[62:63], v[120:121], v[118:119]
	v_pk_fma_f32 v[64:65], v[64:65], v[104:105], v[100:101]
	v_mov_b32_e32 v100, v212
	v_mov_b32_e32 v101, v213
	v_mov_b32_e32 v102, v214
	v_mov_b32_e32 v103, v215
	v_cvt_pk_bf16_f32 v62, v62, v63
	v_cvt_pk_bf16_f32 v63, v64, v65
	v_lshlrev_b32_e32 v64, 16, v106
	v_and_b32_e32 v65, 0xffff0000, v106
	v_pk_mul_f32 v[100:101], v[130:131], v[100:101]
	s_nop 0
	v_pk_fma_f32 v[58:59], v[58:59], v[100:101], v[64:65]
	v_lshlrev_b32_e32 v64, 16, v107
	v_and_b32_e32 v65, 0xffff0000, v107
	v_pk_mul_f32 v[102:103], v[130:131], v[102:103]
	v_cvt_pk_bf16_f32 v58, v58, v59
	v_pk_fma_f32 v[60:61], v[60:61], v[102:103], v[64:65]
	s_nop 0
	v_cvt_pk_bf16_f32 v59, v60, v61
	v_lshlrev_b32_e32 v60, 16, v108
	v_and_b32_e32 v61, 0xffff0000, v108
	v_pk_fma_f32 v[54:55], v[54:55], v[120:121], v[60:61]
	v_lshlrev_b32_e32 v60, 16, v109
	v_and_b32_e32 v61, 0xffff0000, v109
	v_pk_fma_f32 v[56:57], v[56:57], v[104:105], v[60:61]
	v_cvt_pk_bf16_f32 v54, v54, v55
	v_cvt_pk_bf16_f32 v55, v56, v57
	v_lshlrev_b32_e32 v56, 16, v110
	v_and_b32_e32 v57, 0xffff0000, v110
	v_pk_fma_f32 v[50:51], v[50:51], v[100:101], v[56:57]
	v_lshlrev_b32_e32 v56, 16, v111
	v_and_b32_e32 v57, 0xffff0000, v111
	v_pk_fma_f32 v[52:53], v[52:53], v[102:103], v[56:57]
	v_cvt_pk_bf16_f32 v50, v50, v51
	v_cvt_pk_bf16_f32 v51, v52, v53
	v_lshlrev_b32_e32 v52, 16, v112
	v_and_b32_e32 v53, 0xffff0000, v112
	v_pk_fma_f32 v[46:47], v[46:47], v[120:121], v[52:53]
	v_lshlrev_b32_e32 v52, 16, v113
	v_and_b32_e32 v53, 0xffff0000, v113
	v_pk_fma_f32 v[48:49], v[48:49], v[104:105], v[52:53]
	v_cvt_pk_bf16_f32 v46, v46, v47
	v_cvt_pk_bf16_f32 v47, v48, v49
	v_lshlrev_b32_e32 v48, 16, v114
	v_and_b32_e32 v49, 0xffff0000, v114
	v_pk_fma_f32 v[42:43], v[42:43], v[100:101], v[48:49]
	v_lshlrev_b32_e32 v48, 16, v115
	v_and_b32_e32 v49, 0xffff0000, v115
	v_pk_fma_f32 v[44:45], v[44:45], v[102:103], v[48:49]
	v_cvt_pk_bf16_f32 v42, v42, v43
	v_cvt_pk_bf16_f32 v43, v44, v45
	v_lshlrev_b32_e32 v44, 16, v116
	v_and_b32_e32 v45, 0xffff0000, v116
	v_pk_fma_f32 v[38:39], v[38:39], v[120:121], v[44:45]
	v_lshlrev_b32_e32 v44, 16, v117
	v_and_b32_e32 v45, 0xffff0000, v117
	v_pk_fma_f32 v[40:41], v[40:41], v[104:105], v[44:45]
	v_cvt_pk_bf16_f32 v38, v38, v39
	v_cvt_pk_bf16_f32 v39, v40, v41
	v_lshlrev_b32_e32 v40, 16, v98
	v_and_b32_e32 v41, 0xffff0000, v98
	v_pk_fma_f32 v[34:35], v[34:35], v[100:101], v[40:41]
	v_lshlrev_b32_e32 v40, 16, v99
	v_and_b32_e32 v41, 0xffff0000, v99
	v_mov_b32_e32 v98, v216
	v_mov_b32_e32 v99, v217
	v_mov_b32_e32 v100, v218
	v_mov_b32_e32 v101, v219
	v_pk_fma_f32 v[36:37], v[36:37], v[102:103], v[40:41]
	v_cvt_pk_bf16_f32 v34, v34, v35
	v_cvt_pk_bf16_f32 v35, v36, v37
	v_lshlrev_b32_e32 v36, 16, v96
	v_and_b32_e32 v37, 0xffff0000, v96
	v_lshlrev_b32_e32 v44, 16, v97
	v_and_b32_e32 v45, 0xffff0000, v97
	v_lshlrev_b32_e32 v48, 16, v94
	v_and_b32_e32 v49, 0xffff0000, v94
	v_pk_mul_f32 v[40:41], v[130:131], v[98:99]
	s_nop 0
	v_pk_fma_f32 v[30:31], v[30:31], v[40:41], v[36:37]
	v_pk_mul_f32 v[36:37], v[130:131], v[100:101]
	s_nop 0
	v_pk_fma_f32 v[32:33], v[32:33], v[36:37], v[44:45]
	v_cvt_pk_bf16_f32 v44, v30, v31
	v_cvt_pk_bf16_f32 v45, v32, v33
	v_mov_b32_e32 v30, v220
	v_mov_b32_e32 v31, v221
	v_mov_b32_e32 v32, v222
	v_mov_b32_e32 v33, v223
	s_nop 0
	global_store_dwordx2 v[86:87], v[62:63], off
	global_store_dwordx2 v[78:79], v[58:59], off offset:32
	global_store_dwordx2 v[88:89], v[54:55], off
	global_store_dwordx2 v[74:75], v[50:51], off offset:32
	global_store_dwordx2 v[90:91], v[46:47], off
	global_store_dwordx2 v[70:71], v[42:43], off offset:32
	global_store_dwordx2 v[92:93], v[38:39], off
	global_store_dwordx2 v[66:67], v[34:35], off offset:32
	global_store_dwordx2 v[78:79], v[44:45], off offset:256
	v_pk_mul_f32 v[30:31], v[130:131], v[30:31]
	s_nop 0
	v_pk_fma_f32 v[26:27], v[26:27], v[30:31], v[48:49]
	v_lshlrev_b32_e32 v48, 16, v95
	v_and_b32_e32 v49, 0xffff0000, v95
	v_pk_mul_f32 v[32:33], v[130:131], v[32:33]
	v_cvt_pk_bf16_f32 v26, v26, v27
	v_pk_fma_f32 v[28:29], v[28:29], v[32:33], v[48:49]
	s_nop 0
	v_cvt_pk_bf16_f32 v27, v28, v29
	global_store_dwordx2 v[78:79], v[26:27], off offset:288
	v_lshlrev_b32_e32 v26, 16, v84
	v_and_b32_e32 v27, 0xffff0000, v84
	v_pk_fma_f32 v[22:23], v[22:23], v[40:41], v[26:27]
	v_lshlrev_b32_e32 v26, 16, v85
	v_and_b32_e32 v27, 0xffff0000, v85
	v_pk_fma_f32 v[24:25], v[24:25], v[36:37], v[26:27]
	v_cvt_pk_bf16_f32 v22, v22, v23
	v_cvt_pk_bf16_f32 v23, v24, v25
	global_store_dwordx2 v[74:75], v[22:23], off offset:256
	v_lshlrev_b32_e32 v22, 16, v82
	v_and_b32_e32 v23, 0xffff0000, v82
	v_pk_fma_f32 v[18:19], v[18:19], v[30:31], v[22:23]
	v_lshlrev_b32_e32 v22, 16, v83
	v_and_b32_e32 v23, 0xffff0000, v83
	v_pk_fma_f32 v[20:21], v[20:21], v[32:33], v[22:23]
	v_cvt_pk_bf16_f32 v18, v18, v19
	v_cvt_pk_bf16_f32 v19, v20, v21
	global_store_dwordx2 v[74:75], v[18:19], off offset:288
	v_lshlrev_b32_e32 v18, 16, v80
	v_and_b32_e32 v19, 0xffff0000, v80
	v_pk_fma_f32 v[14:15], v[14:15], v[40:41], v[18:19]
	v_lshlrev_b32_e32 v18, 16, v81
	v_and_b32_e32 v19, 0xffff0000, v81
	v_pk_fma_f32 v[16:17], v[16:17], v[36:37], v[18:19]
	v_cvt_pk_bf16_f32 v14, v14, v15
	v_cvt_pk_bf16_f32 v15, v16, v17
	global_store_dwordx2 v[70:71], v[14:15], off offset:256
	v_lshlrev_b32_e32 v14, 16, v76
	v_and_b32_e32 v15, 0xffff0000, v76
	v_pk_fma_f32 v[10:11], v[10:11], v[30:31], v[14:15]
	v_lshlrev_b32_e32 v14, 16, v77
	v_and_b32_e32 v15, 0xffff0000, v77
	v_pk_fma_f32 v[12:13], v[12:13], v[32:33], v[14:15]
	v_cvt_pk_bf16_f32 v10, v10, v11
	v_cvt_pk_bf16_f32 v11, v12, v13
	global_store_dwordx2 v[70:71], v[10:11], off offset:288
	v_lshlrev_b32_e32 v10, 16, v72
	v_and_b32_e32 v11, 0xffff0000, v72
	v_pk_fma_f32 v[6:7], v[6:7], v[40:41], v[10:11]
	v_lshlrev_b32_e32 v10, 16, v73
	v_and_b32_e32 v11, 0xffff0000, v73
	v_pk_fma_f32 v[8:9], v[8:9], v[36:37], v[10:11]
	v_cvt_pk_bf16_f32 v6, v6, v7
	v_cvt_pk_bf16_f32 v7, v8, v9
	global_store_dwordx2 v[66:67], v[6:7], off offset:256
	v_lshlrev_b32_e32 v6, 16, v68
	v_and_b32_e32 v7, 0xffff0000, v68
	v_pk_fma_f32 v[2:3], v[2:3], v[30:31], v[6:7]
	v_lshlrev_b32_e32 v6, 16, v69
	v_and_b32_e32 v7, 0xffff0000, v69
	v_pk_fma_f32 v[138:139], v[4:5], v[32:33], v[6:7]
	v_cvt_pk_bf16_f32 v0, v2, v3
	global_store_dword v[66:67], v0, off offset:288
	s_branch .LBB0_1615
